# compression second layer (combine16_fused): weight-fragment loads 4 in flight instead of one per MFMA (renamed destinations, MFMAs sunk)
# baseline (speedup 1.0000x reference)
.LBB0_1077:
	s_lshl_b32 s8, s2, 8
	s_ashr_i32 s9, s8, 31
	v_mov_b32_e32 v2, v1
	v_mov_b32_e32 v84, v159
	s_lshl_b32 s1, s0, 8
	s_lshl_b64 s[8:9], s[8:9], 2
	s_add_u32 s8, s6, s8
	v_lshl_add_u32 v154, v84, 3, s57
	s_addc_u32 s9, s7, s9
	v_ashrrev_i32_e32 v155, 31, v154
	v_lshl_add_u64 v[152:153], v[154:155], 2, s[8:9]
	global_load_dwordx4 v[84:87], v[152:153], off offset:16
	global_load_dwordx4 v[88:91], v[152:153], off
	s_add_i32 s1, s1, s56
	v_add_u32_e32 v156, s1, v2
	s_movk_i32 s1, 0x2000
	s_cmp_eq_u32 s2, 0
	s_mov_b32 s3, 0x34800000
	s_cselect_b32 s3, s3, 0x35200000
	s_add_u32 s22, s11, s3
	s_addc_u32 s23, s10, 0
	s_ashr_i32 s3, s2, 31
	s_mul_i32 s24, s2, 0x2200000
	s_waitcnt vmcnt(0)
	v_pk_add_f32 v[162:163], v[136:137], v[88:89]
	s_nop 0
	v_mul_f32_e32 v2, 0x3d372713, v162
	v_mul_f32_e32 v2, v162, v2
	v_fma_f32 v2, v162, v2, v162
	v_mul_f32_e32 v2, 0x3f4c422a, v2
	v_mul_f32_e32 v2, -2.0, v2
	v_mul_f32_e32 v2, 0x3fb8aa3b, v2
	v_pk_add_f32 v[136:137], v[134:135], v[86:87]
	v_pk_add_f32 v[134:135], v[132:133], v[84:85]
	v_exp_f32_e32 v132, v2
	v_mul_f32_e32 v2, 0x3d372713, v163
	v_mul_f32_e32 v2, v163, v2
	v_fma_f32 v2, v163, v2, v163
	v_mul_f32_e32 v2, 0x3f4c422a, v2
	v_mul_f32_e32 v2, -2.0, v2
	v_mul_f32_e32 v2, 0x3fb8aa3b, v2
	v_exp_f32_e32 v133, v2
	v_pk_add_f32 v[138:139], v[138:139], v[90:91]
	v_pk_add_f32 v[130:131], v[130:131], v[90:91]
	v_pk_add_f32 v[122:123], v[122:123], v[90:91]
	v_pk_add_f32 v[132:133], v[132:133], 1.0 op_sel_hi:[1,0]
	v_pk_add_f32 v[114:115], v[114:115], v[90:91]
	v_div_scale_f32 v2, s[8:9], v133, v133, v163
	v_rcp_f32_e32 v157, v2
	v_pk_add_f32 v[106:107], v[106:107], v[90:91]
	v_pk_add_f32 v[98:99], v[98:99], v[90:91]
	v_pk_add_f32 v[82:83], v[82:83], v[90:91]
	v_fma_f32 v164, -v2, v157, 1.0
	v_fmac_f32_e32 v157, v164, v157
	v_div_scale_f32 v164, vcc, v163, v133, v163
	v_mul_f32_e32 v165, v164, v157
	v_fma_f32 v166, -v2, v165, v164
	v_fmac_f32_e32 v165, v166, v157
	v_fma_f32 v2, -v2, v165, v164
	v_div_fmas_f32 v2, v2, v157, v165
	v_div_fixup_f32 v2, v2, v133, v163
	v_div_scale_f32 v133, s[8:9], v132, v132, v162
	v_rcp_f32_e32 v157, v133
	v_pk_add_f32 v[74:75], v[74:75], v[90:91]
	v_fma_f32 v163, -v133, v157, 1.0
	v_fmac_f32_e32 v157, v163, v157
	v_div_scale_f32 v163, vcc, v162, v132, v162
	v_mul_f32_e32 v164, v163, v157
	v_fma_f32 v165, -v133, v164, v163
	v_fmac_f32_e32 v164, v165, v157
	v_fma_f32 v133, -v133, v164, v163
	v_div_fmas_f32 v133, v133, v157, v164
	v_div_fixup_f32 v132, v133, v132, v162
	v_cvt_pk_bf16_f32 v132, v132, v2
	v_mul_f32_e32 v2, 0x3d372713, v138
	v_mul_f32_e32 v2, v138, v2
	v_fma_f32 v2, v138, v2, v138
	v_mul_f32_e32 v2, 0x3f4c422a, v2
	v_mul_f32_e32 v2, -2.0, v2
	v_mul_f32_e32 v2, 0x3fb8aa3b, v2
	v_exp_f32_e32 v162, v2
	v_mul_f32_e32 v2, 0x3d372713, v139
	v_mul_f32_e32 v2, v139, v2
	v_fma_f32 v2, v139, v2, v139
	v_mul_f32_e32 v2, 0x3f4c422a, v2
	v_mul_f32_e32 v2, -2.0, v2
	v_mul_f32_e32 v2, 0x3fb8aa3b, v2
	v_exp_f32_e32 v163, v2
	s_nop 0
	v_pk_add_f32 v[162:163], v[162:163], 1.0 op_sel_hi:[1,0]
	s_nop 0
	v_div_scale_f32 v2, s[8:9], v163, v163, v139
	v_rcp_f32_e32 v133, v2
	s_nop 0
	v_fma_f32 v157, -v2, v133, 1.0
	v_fmac_f32_e32 v133, v157, v133
	v_div_scale_f32 v157, vcc, v139, v163, v139
	v_mul_f32_e32 v164, v157, v133
	v_fma_f32 v165, -v2, v164, v157
	v_fmac_f32_e32 v164, v165, v133
	v_fma_f32 v2, -v2, v164, v157
	v_div_fmas_f32 v2, v2, v133, v164
	v_div_scale_f32 v133, s[8:9], v162, v162, v138
	v_div_fixup_f32 v2, v2, v163, v139
	v_rcp_f32_e32 v139, v133
	s_nop 0
	v_fma_f32 v157, -v133, v139, 1.0
	v_fmac_f32_e32 v139, v157, v139
	v_div_scale_f32 v157, vcc, v138, v162, v138
	v_mul_f32_e32 v163, v157, v139
	v_fma_f32 v164, -v133, v163, v157
	v_fmac_f32_e32 v163, v164, v139
	v_fma_f32 v133, -v133, v163, v157
	v_div_fmas_f32 v133, v133, v139, v163
	v_div_fixup_f32 v133, v133, v162, v138
	v_cvt_pk_bf16_f32 v133, v133, v2
	v_mul_f32_e32 v2, 0x3d372713, v134
	v_mul_f32_e32 v2, v134, v2
	v_fma_f32 v2, v134, v2, v134
	v_mul_f32_e32 v2, 0x3f4c422a, v2
	v_mul_f32_e32 v2, -2.0, v2
	v_mul_f32_e32 v2, 0x3fb8aa3b, v2
	v_exp_f32_e32 v138, v2
	v_mul_f32_e32 v2, 0x3d372713, v135
	v_mul_f32_e32 v2, v135, v2
	v_fma_f32 v2, v135, v2, v135
	v_mul_f32_e32 v2, 0x3f4c422a, v2
	v_mul_f32_e32 v2, -2.0, v2
	v_mul_f32_e32 v2, 0x3fb8aa3b, v2
	v_exp_f32_e32 v139, v2
	s_nop 0
	v_pk_add_f32 v[138:139], v[138:139], 1.0 op_sel_hi:[1,0]
	s_nop 0
	v_div_scale_f32 v2, s[8:9], v139, v139, v135
	v_rcp_f32_e32 v157, v2
	s_nop 0
	v_fma_f32 v162, -v2, v157, 1.0
	v_fmac_f32_e32 v157, v162, v157
	v_div_scale_f32 v162, vcc, v135, v139, v135
	v_mul_f32_e32 v163, v162, v157
	v_fma_f32 v164, -v2, v163, v162
	v_fmac_f32_e32 v163, v164, v157
	v_fma_f32 v2, -v2, v163, v162
	v_div_fmas_f32 v2, v2, v157, v163
	v_div_fixup_f32 v2, v2, v139, v135
	v_div_scale_f32 v135, s[8:9], v138, v138, v134
	v_rcp_f32_e32 v139, v135
	s_nop 0
	v_fma_f32 v157, -v135, v139, 1.0
	v_fmac_f32_e32 v139, v157, v139
	v_div_scale_f32 v157, vcc, v134, v138, v134
	v_mul_f32_e32 v162, v157, v139
	v_fma_f32 v163, -v135, v162, v157
	v_fmac_f32_e32 v162, v163, v139
	v_fma_f32 v135, -v135, v162, v157
	v_div_fmas_f32 v135, v135, v139, v162
	v_div_fixup_f32 v134, v135, v138, v134
	v_cvt_pk_bf16_f32 v134, v134, v2
	v_mul_f32_e32 v2, 0x3d372713, v136
	v_mul_f32_e32 v2, v136, v2
	v_fma_f32 v2, v136, v2, v136
	v_mul_f32_e32 v2, 0x3f4c422a, v2
	v_mul_f32_e32 v2, -2.0, v2
	v_mul_f32_e32 v2, 0x3fb8aa3b, v2
	v_exp_f32_e32 v138, v2
	v_mul_f32_e32 v2, 0x3d372713, v137
	v_mul_f32_e32 v2, v137, v2
	v_fma_f32 v2, v137, v2, v137
	v_mul_f32_e32 v2, 0x3f4c422a, v2
	v_mul_f32_e32 v2, -2.0, v2
	v_mul_f32_e32 v2, 0x3fb8aa3b, v2
	v_exp_f32_e32 v139, v2
	s_nop 0
	v_pk_add_f32 v[138:139], v[138:139], 1.0 op_sel_hi:[1,0]
	s_nop 0
	v_div_scale_f32 v2, s[8:9], v139, v139, v137
	v_rcp_f32_e32 v135, v2
	s_nop 0
	v_fma_f32 v157, -v2, v135, 1.0
	v_fmac_f32_e32 v135, v157, v135
	v_div_scale_f32 v157, vcc, v137, v139, v137
	v_mul_f32_e32 v162, v157, v135
	v_fma_f32 v163, -v2, v162, v157
	v_fmac_f32_e32 v162, v163, v135
	v_fma_f32 v2, -v2, v162, v157
	v_div_fmas_f32 v2, v2, v135, v162
	v_div_scale_f32 v135, s[8:9], v138, v138, v136
	v_div_fixup_f32 v2, v2, v139, v137
	v_rcp_f32_e32 v137, v135
	s_nop 0
	v_fma_f32 v139, -v135, v137, 1.0
	v_fmac_f32_e32 v137, v139, v137
	v_div_scale_f32 v139, vcc, v136, v138, v136
	v_mul_f32_e32 v157, v139, v137
	v_fma_f32 v162, -v135, v157, v139
	v_fmac_f32_e32 v157, v162, v137
	v_fma_f32 v135, -v135, v157, v139
	v_div_fmas_f32 v135, v135, v137, v157
	v_ashrrev_i32_e32 v157, 31, v156
	v_div_fixup_f32 v135, v135, v138, v136
	v_lshlrev_b64 v[136:137], 9, v[156:157]
	v_lshl_add_u64 v[136:137], s[20:21], 0, v[136:137]
	v_cvt_pk_bf16_f32 v135, v135, v2
	v_lshl_add_u64 v[136:137], v[154:155], 1, v[136:137]
	global_store_dwordx4 v[136:137], v[132:135], off
	s_nop 1
	v_pk_add_f32 v[132:133], v[128:129], v[88:89]
	v_pk_add_f32 v[128:129], v[126:127], v[86:87]
	v_mul_f32_e32 v2, 0x3d372713, v132
	v_mul_f32_e32 v2, v132, v2
	v_fma_f32 v2, v132, v2, v132
	v_mul_f32_e32 v2, 0x3f4c422a, v2
	v_mul_f32_e32 v2, -2.0, v2
	v_mul_f32_e32 v2, 0x3fb8aa3b, v2
	v_pk_add_f32 v[126:127], v[124:125], v[84:85]
	v_exp_f32_e32 v124, v2
	v_mul_f32_e32 v2, 0x3d372713, v133
	v_mul_f32_e32 v2, v133, v2
	v_fma_f32 v2, v133, v2, v133
	v_mul_f32_e32 v2, 0x3f4c422a, v2
	v_mul_f32_e32 v2, -2.0, v2
	v_mul_f32_e32 v2, 0x3fb8aa3b, v2
	v_exp_f32_e32 v125, v2
	s_nop 0
	v_pk_add_f32 v[124:125], v[124:125], 1.0 op_sel_hi:[1,0]
	s_nop 0
	v_div_scale_f32 v2, s[8:9], v125, v125, v133
	v_rcp_f32_e32 v134, v2
	s_nop 0
	v_fma_f32 v135, -v2, v134, 1.0
	v_fmac_f32_e32 v134, v135, v134
	v_div_scale_f32 v135, vcc, v133, v125, v133
	v_mul_f32_e32 v138, v135, v134
	v_fma_f32 v139, -v2, v138, v135
	v_fmac_f32_e32 v138, v139, v134
	v_fma_f32 v2, -v2, v138, v135
	v_div_fmas_f32 v2, v2, v134, v138
	v_div_fixup_f32 v2, v2, v125, v133
	v_div_scale_f32 v125, s[8:9], v124, v124, v132
	v_rcp_f32_e32 v133, v125
	s_nop 0
	v_fma_f32 v134, -v125, v133, 1.0
	v_fmac_f32_e32 v133, v134, v133
	v_div_scale_f32 v134, vcc, v132, v124, v132
	v_mul_f32_e32 v135, v134, v133
	v_fma_f32 v138, -v125, v135, v134
	v_fmac_f32_e32 v135, v138, v133
	v_fma_f32 v125, -v125, v135, v134
	v_div_fmas_f32 v125, v125, v133, v135
	v_div_fixup_f32 v124, v125, v124, v132
	v_cvt_pk_bf16_f32 v124, v124, v2
	v_mul_f32_e32 v2, 0x3d372713, v130
	v_mul_f32_e32 v2, v130, v2
	v_fma_f32 v2, v130, v2, v130
	v_mul_f32_e32 v2, 0x3f4c422a, v2
	v_mul_f32_e32 v2, -2.0, v2
	v_mul_f32_e32 v2, 0x3fb8aa3b, v2
	v_exp_f32_e32 v132, v2
	v_mul_f32_e32 v2, 0x3d372713, v131
	v_mul_f32_e32 v2, v131, v2
	v_fma_f32 v2, v131, v2, v131
	v_mul_f32_e32 v2, 0x3f4c422a, v2
	v_mul_f32_e32 v2, -2.0, v2
	v_mul_f32_e32 v2, 0x3fb8aa3b, v2
	v_exp_f32_e32 v133, v2
	s_nop 0
	v_pk_add_f32 v[132:133], v[132:133], 1.0 op_sel_hi:[1,0]
	s_nop 0
	v_div_scale_f32 v2, s[8:9], v133, v133, v131
	v_rcp_f32_e32 v125, v2
	s_nop 0
	v_fma_f32 v134, -v2, v125, 1.0
	v_fmac_f32_e32 v125, v134, v125
	v_div_scale_f32 v134, vcc, v131, v133, v131
	v_mul_f32_e32 v135, v134, v125
	v_fma_f32 v138, -v2, v135, v134
	v_fmac_f32_e32 v135, v138, v125
	v_fma_f32 v2, -v2, v135, v134
	v_div_fmas_f32 v2, v2, v125, v135
	v_div_scale_f32 v125, s[8:9], v132, v132, v130
	v_div_fixup_f32 v2, v2, v133, v131
	v_rcp_f32_e32 v131, v125
	s_nop 0
	v_fma_f32 v133, -v125, v131, 1.0
	v_fmac_f32_e32 v131, v133, v131
	v_div_scale_f32 v133, vcc, v130, v132, v130
	v_mul_f32_e32 v134, v133, v131
	v_fma_f32 v135, -v125, v134, v133
	v_fmac_f32_e32 v134, v135, v131
	v_fma_f32 v125, -v125, v134, v133
	v_div_fmas_f32 v125, v125, v131, v134
	v_div_fixup_f32 v125, v125, v132, v130
	v_cvt_pk_bf16_f32 v125, v125, v2
	v_mul_f32_e32 v2, 0x3d372713, v126
	v_mul_f32_e32 v2, v126, v2
	v_fma_f32 v2, v126, v2, v126
	v_mul_f32_e32 v2, 0x3f4c422a, v2
	v_mul_f32_e32 v2, -2.0, v2
	v_mul_f32_e32 v2, 0x3fb8aa3b, v2
	v_exp_f32_e32 v130, v2
	v_mul_f32_e32 v2, 0x3d372713, v127
	v_mul_f32_e32 v2, v127, v2
	v_fma_f32 v2, v127, v2, v127
	v_mul_f32_e32 v2, 0x3f4c422a, v2
	v_mul_f32_e32 v2, -2.0, v2
	v_mul_f32_e32 v2, 0x3fb8aa3b, v2
	v_exp_f32_e32 v131, v2
	s_nop 0
	v_pk_add_f32 v[130:131], v[130:131], 1.0 op_sel_hi:[1,0]
	s_nop 0
	v_div_scale_f32 v2, s[8:9], v131, v131, v127
	v_rcp_f32_e32 v132, v2
	s_nop 0
	v_fma_f32 v133, -v2, v132, 1.0
	v_fmac_f32_e32 v132, v133, v132
	v_div_scale_f32 v133, vcc, v127, v131, v127
	v_mul_f32_e32 v134, v133, v132
	v_fma_f32 v135, -v2, v134, v133
	v_fmac_f32_e32 v134, v135, v132
	v_fma_f32 v2, -v2, v134, v133
	v_div_fmas_f32 v2, v2, v132, v134
	v_div_fixup_f32 v2, v2, v131, v127
	v_div_scale_f32 v127, s[8:9], v130, v130, v126
	v_rcp_f32_e32 v131, v127
	s_nop 0
	v_fma_f32 v132, -v127, v131, 1.0
	v_fmac_f32_e32 v131, v132, v131
	v_div_scale_f32 v132, vcc, v126, v130, v126
	v_mul_f32_e32 v133, v132, v131
	v_fma_f32 v134, -v127, v133, v132
	v_fmac_f32_e32 v133, v134, v131
	v_fma_f32 v127, -v127, v133, v132
	v_div_fmas_f32 v127, v127, v131, v133
	v_div_fixup_f32 v126, v127, v130, v126
	v_cvt_pk_bf16_f32 v126, v126, v2
	v_mul_f32_e32 v2, 0x3d372713, v128
	v_mul_f32_e32 v2, v128, v2
	v_fma_f32 v2, v128, v2, v128
	v_mul_f32_e32 v2, 0x3f4c422a, v2
	v_mul_f32_e32 v2, -2.0, v2
	v_mul_f32_e32 v2, 0x3fb8aa3b, v2
	v_exp_f32_e32 v130, v2
	v_mul_f32_e32 v2, 0x3d372713, v129
	v_mul_f32_e32 v2, v129, v2
	v_fma_f32 v2, v129, v2, v129
	v_mul_f32_e32 v2, 0x3f4c422a, v2
	v_mul_f32_e32 v2, -2.0, v2
	v_mul_f32_e32 v2, 0x3fb8aa3b, v2
	v_exp_f32_e32 v131, v2
	s_nop 0
	v_pk_add_f32 v[130:131], v[130:131], 1.0 op_sel_hi:[1,0]
	s_nop 0
	v_div_scale_f32 v2, s[8:9], v131, v131, v129
	v_rcp_f32_e32 v127, v2
	s_nop 0
	v_fma_f32 v132, -v2, v127, 1.0
	v_fmac_f32_e32 v127, v132, v127
	v_div_scale_f32 v132, vcc, v129, v131, v129
	v_mul_f32_e32 v133, v132, v127
	v_fma_f32 v134, -v2, v133, v132
	v_fmac_f32_e32 v133, v134, v127
	v_fma_f32 v2, -v2, v133, v132
	v_div_fmas_f32 v2, v2, v127, v133
	v_div_scale_f32 v127, s[8:9], v130, v130, v128
	v_div_fixup_f32 v2, v2, v131, v129
	v_rcp_f32_e32 v129, v127
	s_mov_b64 s[8:9], 0x2000
	v_fma_f32 v131, -v127, v129, 1.0
	v_fmac_f32_e32 v129, v131, v129
	v_div_scale_f32 v131, vcc, v128, v130, v128
	v_mul_f32_e32 v132, v131, v129
	v_fma_f32 v133, -v127, v132, v131
	v_fmac_f32_e32 v132, v133, v129
	v_fma_f32 v127, -v127, v132, v131
	v_div_fmas_f32 v127, v127, v129, v132
	v_div_fixup_f32 v127, v127, v130, v128
	v_add_co_u32_e32 v130, vcc, s1, v136
	v_cvt_pk_bf16_f32 v127, v127, v2
	s_nop 0
	v_addc_co_u32_e32 v131, vcc, 0, v137, vcc
	global_store_dwordx4 v[130:131], v[124:127], off
	v_lshl_add_u64 v[128:129], v[136:137], 0, s[8:9]
	s_movk_i32 s1, 0x4000
	v_pk_add_f32 v[124:125], v[120:121], v[88:89]
	v_pk_add_f32 v[120:121], v[118:119], v[86:87]
	v_mul_f32_e32 v2, 0x3d372713, v124
	v_mul_f32_e32 v2, v124, v2
	v_fma_f32 v2, v124, v2, v124
	v_mul_f32_e32 v2, 0x3f4c422a, v2
	v_mul_f32_e32 v2, -2.0, v2
	v_mul_f32_e32 v2, 0x3fb8aa3b, v2
	v_pk_add_f32 v[118:119], v[116:117], v[84:85]
	v_exp_f32_e32 v116, v2
	v_mul_f32_e32 v2, 0x3d372713, v125
	v_mul_f32_e32 v2, v125, v2
	v_fma_f32 v2, v125, v2, v125
	v_mul_f32_e32 v2, 0x3f4c422a, v2
	v_mul_f32_e32 v2, -2.0, v2
	v_mul_f32_e32 v2, 0x3fb8aa3b, v2
	v_exp_f32_e32 v117, v2
	s_nop 0
	v_pk_add_f32 v[116:117], v[116:117], 1.0 op_sel_hi:[1,0]
	s_nop 0
	v_div_scale_f32 v2, s[8:9], v117, v117, v125
	v_rcp_f32_e32 v126, v2
	s_nop 0
	v_fma_f32 v127, -v2, v126, 1.0
	v_fmac_f32_e32 v126, v127, v126
	v_div_scale_f32 v127, vcc, v125, v117, v125
	v_mul_f32_e32 v130, v127, v126
	v_fma_f32 v131, -v2, v130, v127
	v_fmac_f32_e32 v130, v131, v126
	v_fma_f32 v2, -v2, v130, v127
	v_div_fmas_f32 v2, v2, v126, v130
	v_div_fixup_f32 v2, v2, v117, v125
	v_div_scale_f32 v117, s[8:9], v116, v116, v124
	v_rcp_f32_e32 v125, v117
	s_nop 0
	v_fma_f32 v126, -v117, v125, 1.0
	v_fmac_f32_e32 v125, v126, v125
	v_div_scale_f32 v126, vcc, v124, v116, v124
	v_mul_f32_e32 v127, v126, v125
	v_fma_f32 v130, -v117, v127, v126
	v_fmac_f32_e32 v127, v130, v125
	v_fma_f32 v117, -v117, v127, v126
	v_div_fmas_f32 v117, v117, v125, v127
	v_div_fixup_f32 v116, v117, v116, v124
	v_cvt_pk_bf16_f32 v116, v116, v2
	v_mul_f32_e32 v2, 0x3d372713, v122
	v_mul_f32_e32 v2, v122, v2
	v_fma_f32 v2, v122, v2, v122
	v_mul_f32_e32 v2, 0x3f4c422a, v2
	v_mul_f32_e32 v2, -2.0, v2
	v_mul_f32_e32 v2, 0x3fb8aa3b, v2
	v_exp_f32_e32 v124, v2
	v_mul_f32_e32 v2, 0x3d372713, v123
	v_mul_f32_e32 v2, v123, v2
	v_fma_f32 v2, v123, v2, v123
	v_mul_f32_e32 v2, 0x3f4c422a, v2
	v_mul_f32_e32 v2, -2.0, v2
	v_mul_f32_e32 v2, 0x3fb8aa3b, v2
	v_exp_f32_e32 v125, v2
	s_nop 0
	v_pk_add_f32 v[124:125], v[124:125], 1.0 op_sel_hi:[1,0]
	s_nop 0
	v_div_scale_f32 v2, s[8:9], v125, v125, v123
	v_rcp_f32_e32 v117, v2
	s_nop 0
	v_fma_f32 v126, -v2, v117, 1.0
	v_fmac_f32_e32 v117, v126, v117
	v_div_scale_f32 v126, vcc, v123, v125, v123
	v_mul_f32_e32 v127, v126, v117
	v_fma_f32 v130, -v2, v127, v126
	v_fmac_f32_e32 v127, v130, v117
	v_fma_f32 v2, -v2, v127, v126
	v_div_fmas_f32 v2, v2, v117, v127
	v_div_scale_f32 v117, s[8:9], v124, v124, v122
	v_div_fixup_f32 v2, v2, v125, v123
	v_rcp_f32_e32 v123, v117
	s_nop 0
	v_fma_f32 v125, -v117, v123, 1.0
	v_fmac_f32_e32 v123, v125, v123
	v_div_scale_f32 v125, vcc, v122, v124, v122
	v_mul_f32_e32 v126, v125, v123
	v_fma_f32 v127, -v117, v126, v125
	v_fmac_f32_e32 v126, v127, v123
	v_fma_f32 v117, -v117, v126, v125
	v_div_fmas_f32 v117, v117, v123, v126
	v_div_fixup_f32 v117, v117, v124, v122
	v_cvt_pk_bf16_f32 v117, v117, v2
	v_mul_f32_e32 v2, 0x3d372713, v118
	v_mul_f32_e32 v2, v118, v2
	v_fma_f32 v2, v118, v2, v118
	v_mul_f32_e32 v2, 0x3f4c422a, v2
	v_mul_f32_e32 v2, -2.0, v2
	v_mul_f32_e32 v2, 0x3fb8aa3b, v2
	v_exp_f32_e32 v122, v2
	v_mul_f32_e32 v2, 0x3d372713, v119
	v_mul_f32_e32 v2, v119, v2
	v_fma_f32 v2, v119, v2, v119
	v_mul_f32_e32 v2, 0x3f4c422a, v2
	v_mul_f32_e32 v2, -2.0, v2
	v_mul_f32_e32 v2, 0x3fb8aa3b, v2
	v_exp_f32_e32 v123, v2
	s_nop 0
	v_pk_add_f32 v[122:123], v[122:123], 1.0 op_sel_hi:[1,0]
	s_nop 0
	v_div_scale_f32 v2, s[8:9], v123, v123, v119
	v_rcp_f32_e32 v124, v2
	s_nop 0
	v_fma_f32 v125, -v2, v124, 1.0
	v_fmac_f32_e32 v124, v125, v124
	v_div_scale_f32 v125, vcc, v119, v123, v119
	v_mul_f32_e32 v126, v125, v124
	v_fma_f32 v127, -v2, v126, v125
	v_fmac_f32_e32 v126, v127, v124
	v_fma_f32 v2, -v2, v126, v125
	v_div_fmas_f32 v2, v2, v124, v126
	v_div_fixup_f32 v2, v2, v123, v119
	v_div_scale_f32 v119, s[8:9], v122, v122, v118
	v_rcp_f32_e32 v123, v119
	s_nop 0
	v_fma_f32 v124, -v119, v123, 1.0
	v_fmac_f32_e32 v123, v124, v123
	v_div_scale_f32 v124, vcc, v118, v122, v118
	v_mul_f32_e32 v125, v124, v123
	v_fma_f32 v126, -v119, v125, v124
	v_fmac_f32_e32 v125, v126, v123
	v_fma_f32 v119, -v119, v125, v124
	v_div_fmas_f32 v119, v119, v123, v125
	v_div_fixup_f32 v118, v119, v122, v118
	v_cvt_pk_bf16_f32 v118, v118, v2
	v_mul_f32_e32 v2, 0x3d372713, v120
	v_mul_f32_e32 v2, v120, v2
	v_fma_f32 v2, v120, v2, v120
	v_mul_f32_e32 v2, 0x3f4c422a, v2
	v_mul_f32_e32 v2, -2.0, v2
	v_mul_f32_e32 v2, 0x3fb8aa3b, v2
	v_exp_f32_e32 v122, v2
	v_mul_f32_e32 v2, 0x3d372713, v121
	v_mul_f32_e32 v2, v121, v2
	v_fma_f32 v2, v121, v2, v121
	v_mul_f32_e32 v2, 0x3f4c422a, v2
	v_mul_f32_e32 v2, -2.0, v2
	v_mul_f32_e32 v2, 0x3fb8aa3b, v2
	v_exp_f32_e32 v123, v2
	s_nop 0
	v_pk_add_f32 v[122:123], v[122:123], 1.0 op_sel_hi:[1,0]
	s_nop 0
	v_div_scale_f32 v2, s[8:9], v123, v123, v121
	v_rcp_f32_e32 v119, v2
	s_nop 0
	v_fma_f32 v124, -v2, v119, 1.0
	v_fmac_f32_e32 v119, v124, v119
	v_div_scale_f32 v124, vcc, v121, v123, v121
	v_mul_f32_e32 v125, v124, v119
	v_fma_f32 v126, -v2, v125, v124
	v_fmac_f32_e32 v125, v126, v119
	v_fma_f32 v2, -v2, v125, v124
	v_div_fmas_f32 v2, v2, v119, v125
	v_div_scale_f32 v119, s[8:9], v122, v122, v120
	v_div_fixup_f32 v2, v2, v123, v121
	v_rcp_f32_e32 v121, v119
	s_mov_b64 s[8:9], 0x4000
	v_fma_f32 v123, -v119, v121, 1.0
	v_fmac_f32_e32 v121, v123, v121
	v_div_scale_f32 v123, vcc, v120, v122, v120
	v_mul_f32_e32 v124, v123, v121
	v_fma_f32 v125, -v119, v124, v123
	v_fmac_f32_e32 v124, v125, v121
	v_fma_f32 v119, -v119, v124, v123
	v_div_fmas_f32 v119, v119, v121, v124
	v_div_fixup_f32 v119, v119, v122, v120
	v_add_co_u32_e32 v122, vcc, s1, v136
	v_cvt_pk_bf16_f32 v119, v119, v2
	s_nop 0
	v_addc_co_u32_e32 v123, vcc, 0, v137, vcc
	global_store_dwordx4 v[122:123], v[116:119], off
	v_lshl_add_u64 v[120:121], v[136:137], 0, s[8:9]
	s_movk_i32 s1, 0x6000
	v_pk_add_f32 v[116:117], v[112:113], v[88:89]
	v_pk_add_f32 v[112:113], v[110:111], v[86:87]
	v_mul_f32_e32 v2, 0x3d372713, v116
	v_mul_f32_e32 v2, v116, v2
	v_fma_f32 v2, v116, v2, v116
	v_mul_f32_e32 v2, 0x3f4c422a, v2
	v_mul_f32_e32 v2, -2.0, v2
	v_mul_f32_e32 v2, 0x3fb8aa3b, v2
	v_pk_add_f32 v[110:111], v[108:109], v[84:85]
	v_exp_f32_e32 v108, v2
	v_mul_f32_e32 v2, 0x3d372713, v117
	v_mul_f32_e32 v2, v117, v2
	v_fma_f32 v2, v117, v2, v117
	v_mul_f32_e32 v2, 0x3f4c422a, v2
	v_mul_f32_e32 v2, -2.0, v2
	v_mul_f32_e32 v2, 0x3fb8aa3b, v2
	v_exp_f32_e32 v109, v2
	s_nop 0
	v_pk_add_f32 v[108:109], v[108:109], 1.0 op_sel_hi:[1,0]
	s_nop 0
	v_div_scale_f32 v2, s[8:9], v109, v109, v117
	v_rcp_f32_e32 v118, v2
	s_nop 0
	v_fma_f32 v119, -v2, v118, 1.0
	v_fmac_f32_e32 v118, v119, v118
	v_div_scale_f32 v119, vcc, v117, v109, v117
	v_mul_f32_e32 v122, v119, v118
	v_fma_f32 v123, -v2, v122, v119
	v_fmac_f32_e32 v122, v123, v118
	v_fma_f32 v2, -v2, v122, v119
	v_div_fmas_f32 v2, v2, v118, v122
	v_div_fixup_f32 v2, v2, v109, v117
	v_div_scale_f32 v109, s[8:9], v108, v108, v116
	v_rcp_f32_e32 v117, v109
	s_nop 0
	v_fma_f32 v118, -v109, v117, 1.0
	v_fmac_f32_e32 v117, v118, v117
	v_div_scale_f32 v118, vcc, v116, v108, v116
	v_mul_f32_e32 v119, v118, v117
	v_fma_f32 v122, -v109, v119, v118
	v_fmac_f32_e32 v119, v122, v117
	v_fma_f32 v109, -v109, v119, v118
	v_div_fmas_f32 v109, v109, v117, v119
	v_div_fixup_f32 v108, v109, v108, v116
	v_cvt_pk_bf16_f32 v108, v108, v2
	v_mul_f32_e32 v2, 0x3d372713, v114
	v_mul_f32_e32 v2, v114, v2
	v_fma_f32 v2, v114, v2, v114
	v_mul_f32_e32 v2, 0x3f4c422a, v2
	v_mul_f32_e32 v2, -2.0, v2
	v_mul_f32_e32 v2, 0x3fb8aa3b, v2
	v_exp_f32_e32 v116, v2
	v_mul_f32_e32 v2, 0x3d372713, v115
	v_mul_f32_e32 v2, v115, v2
	v_fma_f32 v2, v115, v2, v115
	v_mul_f32_e32 v2, 0x3f4c422a, v2
	v_mul_f32_e32 v2, -2.0, v2
	v_mul_f32_e32 v2, 0x3fb8aa3b, v2
	v_exp_f32_e32 v117, v2
	s_nop 0
	v_pk_add_f32 v[116:117], v[116:117], 1.0 op_sel_hi:[1,0]
	s_nop 0
	v_div_scale_f32 v2, s[8:9], v117, v117, v115
	v_rcp_f32_e32 v109, v2
	s_nop 0
	v_fma_f32 v118, -v2, v109, 1.0
	v_fmac_f32_e32 v109, v118, v109
	v_div_scale_f32 v118, vcc, v115, v117, v115
	v_mul_f32_e32 v119, v118, v109
	v_fma_f32 v122, -v2, v119, v118
	v_fmac_f32_e32 v119, v122, v109
	v_fma_f32 v2, -v2, v119, v118
	v_div_fmas_f32 v2, v2, v109, v119
	v_div_scale_f32 v109, s[8:9], v116, v116, v114
	v_div_fixup_f32 v2, v2, v117, v115
	v_rcp_f32_e32 v115, v109
	s_nop 0
	v_fma_f32 v117, -v109, v115, 1.0
	v_fmac_f32_e32 v115, v117, v115
	v_div_scale_f32 v117, vcc, v114, v116, v114
	v_mul_f32_e32 v118, v117, v115
	v_fma_f32 v119, -v109, v118, v117
	v_fmac_f32_e32 v118, v119, v115
	v_fma_f32 v109, -v109, v118, v117
	v_div_fmas_f32 v109, v109, v115, v118
	v_div_fixup_f32 v109, v109, v116, v114
	v_cvt_pk_bf16_f32 v109, v109, v2
	v_mul_f32_e32 v2, 0x3d372713, v110
	v_mul_f32_e32 v2, v110, v2
	v_fma_f32 v2, v110, v2, v110
	v_mul_f32_e32 v2, 0x3f4c422a, v2
	v_mul_f32_e32 v2, -2.0, v2
	v_mul_f32_e32 v2, 0x3fb8aa3b, v2
	v_exp_f32_e32 v114, v2
	v_mul_f32_e32 v2, 0x3d372713, v111
	v_mul_f32_e32 v2, v111, v2
	v_fma_f32 v2, v111, v2, v111
	v_mul_f32_e32 v2, 0x3f4c422a, v2
	v_mul_f32_e32 v2, -2.0, v2
	v_mul_f32_e32 v2, 0x3fb8aa3b, v2
	v_exp_f32_e32 v115, v2
	s_nop 0
	v_pk_add_f32 v[114:115], v[114:115], 1.0 op_sel_hi:[1,0]
	s_nop 0
	v_div_scale_f32 v2, s[8:9], v115, v115, v111
	v_rcp_f32_e32 v116, v2
	s_nop 0
	v_fma_f32 v117, -v2, v116, 1.0
	v_fmac_f32_e32 v116, v117, v116
	v_div_scale_f32 v117, vcc, v111, v115, v111
	v_mul_f32_e32 v118, v117, v116
	v_fma_f32 v119, -v2, v118, v117
	v_fmac_f32_e32 v118, v119, v116
	v_fma_f32 v2, -v2, v118, v117
	v_div_fmas_f32 v2, v2, v116, v118
	v_div_fixup_f32 v2, v2, v115, v111
	v_div_scale_f32 v111, s[8:9], v114, v114, v110
	v_rcp_f32_e32 v115, v111
	s_nop 0
	v_fma_f32 v116, -v111, v115, 1.0
	v_fmac_f32_e32 v115, v116, v115
	v_div_scale_f32 v116, vcc, v110, v114, v110
	v_mul_f32_e32 v117, v116, v115
	v_fma_f32 v118, -v111, v117, v116
	v_fmac_f32_e32 v117, v118, v115
	v_fma_f32 v111, -v111, v117, v116
	v_div_fmas_f32 v111, v111, v115, v117
	v_div_fixup_f32 v110, v111, v114, v110
	v_cvt_pk_bf16_f32 v110, v110, v2
	v_mul_f32_e32 v2, 0x3d372713, v112
	v_mul_f32_e32 v2, v112, v2
	v_fma_f32 v2, v112, v2, v112
	v_mul_f32_e32 v2, 0x3f4c422a, v2
	v_mul_f32_e32 v2, -2.0, v2
	v_mul_f32_e32 v2, 0x3fb8aa3b, v2
	v_exp_f32_e32 v114, v2
	v_mul_f32_e32 v2, 0x3d372713, v113
	v_mul_f32_e32 v2, v113, v2
	v_fma_f32 v2, v113, v2, v113
	v_mul_f32_e32 v2, 0x3f4c422a, v2
	v_mul_f32_e32 v2, -2.0, v2
	v_mul_f32_e32 v2, 0x3fb8aa3b, v2
	v_exp_f32_e32 v115, v2
	s_nop 0
	v_pk_add_f32 v[114:115], v[114:115], 1.0 op_sel_hi:[1,0]
	s_nop 0
	v_div_scale_f32 v2, s[8:9], v115, v115, v113
	v_rcp_f32_e32 v111, v2
	s_nop 0
	v_fma_f32 v116, -v2, v111, 1.0
	v_fmac_f32_e32 v111, v116, v111
	v_div_scale_f32 v116, vcc, v113, v115, v113
	v_mul_f32_e32 v117, v116, v111
	v_fma_f32 v118, -v2, v117, v116
	v_fmac_f32_e32 v117, v118, v111
	v_fma_f32 v2, -v2, v117, v116
	v_div_fmas_f32 v2, v2, v111, v117
	v_div_scale_f32 v111, s[8:9], v114, v114, v112
	v_div_fixup_f32 v2, v2, v115, v113
	v_rcp_f32_e32 v113, v111
	s_mov_b64 s[8:9], 0x6000
	v_fma_f32 v115, -v111, v113, 1.0
	v_fmac_f32_e32 v113, v115, v113
	v_div_scale_f32 v115, vcc, v112, v114, v112
	v_mul_f32_e32 v116, v115, v113
	v_fma_f32 v117, -v111, v116, v115
	v_fmac_f32_e32 v116, v117, v113
	v_fma_f32 v111, -v111, v116, v115
	v_div_fmas_f32 v111, v111, v113, v116
	v_div_fixup_f32 v111, v111, v114, v112
	v_add_co_u32_e32 v114, vcc, s1, v136
	v_cvt_pk_bf16_f32 v111, v111, v2
	s_nop 0
	v_addc_co_u32_e32 v115, vcc, 0, v137, vcc
	global_store_dwordx4 v[114:115], v[108:111], off
	v_lshl_add_u64 v[112:113], v[136:137], 0, s[8:9]
	s_mov_b32 s1, 0x10000
	v_pk_add_f32 v[108:109], v[104:105], v[88:89]
	v_pk_add_f32 v[104:105], v[102:103], v[86:87]
	v_mul_f32_e32 v2, 0x3d372713, v108
	v_mul_f32_e32 v2, v108, v2
	v_fma_f32 v2, v108, v2, v108
	v_mul_f32_e32 v2, 0x3f4c422a, v2
	v_mul_f32_e32 v2, -2.0, v2
	v_mul_f32_e32 v2, 0x3fb8aa3b, v2
	v_pk_add_f32 v[102:103], v[100:101], v[84:85]
	v_exp_f32_e32 v100, v2
	v_mul_f32_e32 v2, 0x3d372713, v109
	v_mul_f32_e32 v2, v109, v2
	v_fma_f32 v2, v109, v2, v109
	v_mul_f32_e32 v2, 0x3f4c422a, v2
	v_mul_f32_e32 v2, -2.0, v2
	v_mul_f32_e32 v2, 0x3fb8aa3b, v2
	v_exp_f32_e32 v101, v2
	s_nop 0
	v_pk_add_f32 v[100:101], v[100:101], 1.0 op_sel_hi:[1,0]
	s_nop 0
	v_div_scale_f32 v2, s[8:9], v101, v101, v109
	v_rcp_f32_e32 v110, v2
	s_nop 0
	v_fma_f32 v111, -v2, v110, 1.0
	v_fmac_f32_e32 v110, v111, v110
	v_div_scale_f32 v111, vcc, v109, v101, v109
	v_mul_f32_e32 v114, v111, v110
	v_fma_f32 v115, -v2, v114, v111
	v_fmac_f32_e32 v114, v115, v110
	v_fma_f32 v2, -v2, v114, v111
	v_div_fmas_f32 v2, v2, v110, v114
	v_div_fixup_f32 v2, v2, v101, v109
	v_div_scale_f32 v101, s[8:9], v100, v100, v108
	v_rcp_f32_e32 v109, v101
	s_nop 0
	v_fma_f32 v110, -v101, v109, 1.0
	v_fmac_f32_e32 v109, v110, v109
	v_div_scale_f32 v110, vcc, v108, v100, v108
	v_mul_f32_e32 v111, v110, v109
	v_fma_f32 v114, -v101, v111, v110
	v_fmac_f32_e32 v111, v114, v109
	v_fma_f32 v101, -v101, v111, v110
	v_div_fmas_f32 v101, v101, v109, v111
	v_div_fixup_f32 v100, v101, v100, v108
	v_cvt_pk_bf16_f32 v100, v100, v2
	v_mul_f32_e32 v2, 0x3d372713, v106
	v_mul_f32_e32 v2, v106, v2
	v_fma_f32 v2, v106, v2, v106
	v_mul_f32_e32 v2, 0x3f4c422a, v2
	v_mul_f32_e32 v2, -2.0, v2
	v_mul_f32_e32 v2, 0x3fb8aa3b, v2
	v_exp_f32_e32 v108, v2
	v_mul_f32_e32 v2, 0x3d372713, v107
	v_mul_f32_e32 v2, v107, v2
	v_fma_f32 v2, v107, v2, v107
	v_mul_f32_e32 v2, 0x3f4c422a, v2
	v_mul_f32_e32 v2, -2.0, v2
	v_mul_f32_e32 v2, 0x3fb8aa3b, v2
	v_exp_f32_e32 v109, v2
	s_nop 0
	v_pk_add_f32 v[108:109], v[108:109], 1.0 op_sel_hi:[1,0]
	s_nop 0
	v_div_scale_f32 v2, s[8:9], v109, v109, v107
	v_rcp_f32_e32 v101, v2
	s_nop 0
	v_fma_f32 v110, -v2, v101, 1.0
	v_fmac_f32_e32 v101, v110, v101
	v_div_scale_f32 v110, vcc, v107, v109, v107
	v_mul_f32_e32 v111, v110, v101
	v_fma_f32 v114, -v2, v111, v110
	v_fmac_f32_e32 v111, v114, v101
	v_fma_f32 v2, -v2, v111, v110
	v_div_fmas_f32 v2, v2, v101, v111
	v_div_scale_f32 v101, s[8:9], v108, v108, v106
	v_div_fixup_f32 v2, v2, v109, v107
	v_rcp_f32_e32 v107, v101
	s_nop 0
	v_fma_f32 v109, -v101, v107, 1.0
	v_fmac_f32_e32 v107, v109, v107
	v_div_scale_f32 v109, vcc, v106, v108, v106
	v_mul_f32_e32 v110, v109, v107
	v_fma_f32 v111, -v101, v110, v109
	v_fmac_f32_e32 v110, v111, v107
	v_fma_f32 v101, -v101, v110, v109
	v_div_fmas_f32 v101, v101, v107, v110
	v_div_fixup_f32 v101, v101, v108, v106
	v_cvt_pk_bf16_f32 v101, v101, v2
	v_mul_f32_e32 v2, 0x3d372713, v102
	v_mul_f32_e32 v2, v102, v2
	v_fma_f32 v2, v102, v2, v102
	v_mul_f32_e32 v2, 0x3f4c422a, v2
	v_mul_f32_e32 v2, -2.0, v2
	v_mul_f32_e32 v2, 0x3fb8aa3b, v2
	v_exp_f32_e32 v106, v2
	v_mul_f32_e32 v2, 0x3d372713, v103
	v_mul_f32_e32 v2, v103, v2
	v_fma_f32 v2, v103, v2, v103
	v_mul_f32_e32 v2, 0x3f4c422a, v2
	v_mul_f32_e32 v2, -2.0, v2
	v_mul_f32_e32 v2, 0x3fb8aa3b, v2
	v_exp_f32_e32 v107, v2
	s_nop 0
	v_pk_add_f32 v[106:107], v[106:107], 1.0 op_sel_hi:[1,0]
	s_nop 0
	v_div_scale_f32 v2, s[8:9], v107, v107, v103
	v_rcp_f32_e32 v108, v2
	s_nop 0
	v_fma_f32 v109, -v2, v108, 1.0
	v_fmac_f32_e32 v108, v109, v108
	v_div_scale_f32 v109, vcc, v103, v107, v103
	v_mul_f32_e32 v110, v109, v108
	v_fma_f32 v111, -v2, v110, v109
	v_fmac_f32_e32 v110, v111, v108
	v_fma_f32 v2, -v2, v110, v109
	v_div_fmas_f32 v2, v2, v108, v110
	v_div_fixup_f32 v2, v2, v107, v103
	v_div_scale_f32 v103, s[8:9], v106, v106, v102
	v_rcp_f32_e32 v107, v103
	s_nop 0
	v_fma_f32 v108, -v103, v107, 1.0
	v_fmac_f32_e32 v107, v108, v107
	v_div_scale_f32 v108, vcc, v102, v106, v102
	v_mul_f32_e32 v109, v108, v107
	v_fma_f32 v110, -v103, v109, v108
	v_fmac_f32_e32 v109, v110, v107
	v_fma_f32 v103, -v103, v109, v108
	v_div_fmas_f32 v103, v103, v107, v109
	v_div_fixup_f32 v102, v103, v106, v102
	v_cvt_pk_bf16_f32 v102, v102, v2
	v_mul_f32_e32 v2, 0x3d372713, v104
	v_mul_f32_e32 v2, v104, v2
	v_fma_f32 v2, v104, v2, v104
	v_mul_f32_e32 v2, 0x3f4c422a, v2
	v_mul_f32_e32 v2, -2.0, v2
	v_mul_f32_e32 v2, 0x3fb8aa3b, v2
	v_exp_f32_e32 v106, v2
	v_mul_f32_e32 v2, 0x3d372713, v105
	v_mul_f32_e32 v2, v105, v2
	v_fma_f32 v2, v105, v2, v105
	v_mul_f32_e32 v2, 0x3f4c422a, v2
	v_mul_f32_e32 v2, -2.0, v2
	v_mul_f32_e32 v2, 0x3fb8aa3b, v2
	v_exp_f32_e32 v107, v2
	s_nop 0
	v_pk_add_f32 v[106:107], v[106:107], 1.0 op_sel_hi:[1,0]
	s_nop 0
	v_div_scale_f32 v2, s[8:9], v107, v107, v105
	v_rcp_f32_e32 v103, v2
	s_nop 0
	v_fma_f32 v108, -v2, v103, 1.0
	v_fmac_f32_e32 v103, v108, v103
	v_div_scale_f32 v108, vcc, v105, v107, v105
	v_mul_f32_e32 v109, v108, v103
	v_fma_f32 v110, -v2, v109, v108
	v_fmac_f32_e32 v109, v110, v103
	v_fma_f32 v2, -v2, v109, v108
	v_div_fmas_f32 v2, v2, v103, v109
	v_div_scale_f32 v103, s[8:9], v106, v106, v104
	v_div_fixup_f32 v2, v2, v107, v105
	v_rcp_f32_e32 v105, v103
	s_mov_b64 s[8:9], 0x10000
	v_fma_f32 v107, -v103, v105, 1.0
	v_fmac_f32_e32 v105, v107, v105
	v_div_scale_f32 v107, vcc, v104, v106, v104
	v_mul_f32_e32 v108, v107, v105
	v_fma_f32 v109, -v103, v108, v107
	v_fmac_f32_e32 v108, v109, v105
	v_fma_f32 v103, -v103, v108, v107
	v_div_fmas_f32 v103, v103, v105, v108
	v_div_fixup_f32 v103, v103, v106, v104
	v_add_co_u32_e32 v106, vcc, s1, v136
	v_cvt_pk_bf16_f32 v103, v103, v2
	s_nop 0
	v_addc_co_u32_e32 v107, vcc, 0, v137, vcc
	global_store_dwordx4 v[106:107], v[100:103], off
	v_lshl_add_u64 v[104:105], v[136:137], 0, s[8:9]
	s_mov_b32 s1, 0x12000
	v_pk_add_f32 v[100:101], v[96:97], v[88:89]
	v_pk_add_f32 v[96:97], v[94:95], v[86:87]
	v_mul_f32_e32 v2, 0x3d372713, v100
	v_mul_f32_e32 v2, v100, v2
	v_fma_f32 v2, v100, v2, v100
	v_mul_f32_e32 v2, 0x3f4c422a, v2
	v_mul_f32_e32 v2, -2.0, v2
	v_mul_f32_e32 v2, 0x3fb8aa3b, v2
	v_pk_add_f32 v[94:95], v[92:93], v[84:85]
	v_exp_f32_e32 v92, v2
	v_mul_f32_e32 v2, 0x3d372713, v101
	v_mul_f32_e32 v2, v101, v2
	v_fma_f32 v2, v101, v2, v101
	v_mul_f32_e32 v2, 0x3f4c422a, v2
	v_mul_f32_e32 v2, -2.0, v2
	v_mul_f32_e32 v2, 0x3fb8aa3b, v2
	v_exp_f32_e32 v93, v2
	s_nop 0
	v_pk_add_f32 v[92:93], v[92:93], 1.0 op_sel_hi:[1,0]
	s_nop 0
	v_div_scale_f32 v2, s[8:9], v93, v93, v101
	v_rcp_f32_e32 v102, v2
	s_nop 0
	v_fma_f32 v103, -v2, v102, 1.0
	v_fmac_f32_e32 v102, v103, v102
	v_div_scale_f32 v103, vcc, v101, v93, v101
	v_mul_f32_e32 v106, v103, v102
	v_fma_f32 v107, -v2, v106, v103
	v_fmac_f32_e32 v106, v107, v102
	v_fma_f32 v2, -v2, v106, v103
	v_div_fmas_f32 v2, v2, v102, v106
	v_div_fixup_f32 v2, v2, v93, v101
	v_div_scale_f32 v93, s[8:9], v92, v92, v100
	v_rcp_f32_e32 v101, v93
	s_nop 0
	v_fma_f32 v102, -v93, v101, 1.0
	v_fmac_f32_e32 v101, v102, v101
	v_div_scale_f32 v102, vcc, v100, v92, v100
	v_mul_f32_e32 v103, v102, v101
	v_fma_f32 v106, -v93, v103, v102
	v_fmac_f32_e32 v103, v106, v101
	v_fma_f32 v93, -v93, v103, v102
	v_div_fmas_f32 v93, v93, v101, v103
	v_div_fixup_f32 v92, v93, v92, v100
	v_cvt_pk_bf16_f32 v92, v92, v2
	v_mul_f32_e32 v2, 0x3d372713, v98
	v_mul_f32_e32 v2, v98, v2
	v_fma_f32 v2, v98, v2, v98
	v_mul_f32_e32 v2, 0x3f4c422a, v2
	v_mul_f32_e32 v2, -2.0, v2
	v_mul_f32_e32 v2, 0x3fb8aa3b, v2
	v_exp_f32_e32 v100, v2
	v_mul_f32_e32 v2, 0x3d372713, v99
	v_mul_f32_e32 v2, v99, v2
	v_fma_f32 v2, v99, v2, v99
	v_mul_f32_e32 v2, 0x3f4c422a, v2
	v_mul_f32_e32 v2, -2.0, v2
	v_mul_f32_e32 v2, 0x3fb8aa3b, v2
	v_exp_f32_e32 v101, v2
	s_nop 0
	v_pk_add_f32 v[100:101], v[100:101], 1.0 op_sel_hi:[1,0]
	s_nop 0
	v_div_scale_f32 v2, s[8:9], v101, v101, v99
	v_rcp_f32_e32 v93, v2
	s_nop 0
	v_fma_f32 v102, -v2, v93, 1.0
	v_fmac_f32_e32 v93, v102, v93
	v_div_scale_f32 v102, vcc, v99, v101, v99
	v_mul_f32_e32 v103, v102, v93
	v_fma_f32 v106, -v2, v103, v102
	v_fmac_f32_e32 v103, v106, v93
	v_fma_f32 v2, -v2, v103, v102
	v_div_fmas_f32 v2, v2, v93, v103
	v_div_scale_f32 v93, s[8:9], v100, v100, v98
	v_div_fixup_f32 v2, v2, v101, v99
	v_rcp_f32_e32 v99, v93
	s_nop 0
	v_fma_f32 v101, -v93, v99, 1.0
	v_fmac_f32_e32 v99, v101, v99
	v_div_scale_f32 v101, vcc, v98, v100, v98
	v_mul_f32_e32 v102, v101, v99
	v_fma_f32 v103, -v93, v102, v101
	v_fmac_f32_e32 v102, v103, v99
	v_fma_f32 v93, -v93, v102, v101
	v_div_fmas_f32 v93, v93, v99, v102
	v_div_fixup_f32 v93, v93, v100, v98
	v_cvt_pk_bf16_f32 v93, v93, v2
	v_mul_f32_e32 v2, 0x3d372713, v94
	v_mul_f32_e32 v2, v94, v2
	v_fma_f32 v2, v94, v2, v94
	v_mul_f32_e32 v2, 0x3f4c422a, v2
	v_mul_f32_e32 v2, -2.0, v2
	v_mul_f32_e32 v2, 0x3fb8aa3b, v2
	v_exp_f32_e32 v98, v2
	v_mul_f32_e32 v2, 0x3d372713, v95
	v_mul_f32_e32 v2, v95, v2
	v_fma_f32 v2, v95, v2, v95
	v_mul_f32_e32 v2, 0x3f4c422a, v2
	v_mul_f32_e32 v2, -2.0, v2
	v_mul_f32_e32 v2, 0x3fb8aa3b, v2
	v_exp_f32_e32 v99, v2
	s_nop 0
	v_pk_add_f32 v[98:99], v[98:99], 1.0 op_sel_hi:[1,0]
	s_nop 0
	v_div_scale_f32 v2, s[8:9], v99, v99, v95
	v_rcp_f32_e32 v100, v2
	s_nop 0
	v_fma_f32 v101, -v2, v100, 1.0
	v_fmac_f32_e32 v100, v101, v100
	v_div_scale_f32 v101, vcc, v95, v99, v95
	v_mul_f32_e32 v102, v101, v100
	v_fma_f32 v103, -v2, v102, v101
	v_fmac_f32_e32 v102, v103, v100
	v_fma_f32 v2, -v2, v102, v101
	v_div_fmas_f32 v2, v2, v100, v102
	v_div_fixup_f32 v2, v2, v99, v95
	v_div_scale_f32 v95, s[8:9], v98, v98, v94
	v_rcp_f32_e32 v99, v95
	s_nop 0
	v_fma_f32 v100, -v95, v99, 1.0
	v_fmac_f32_e32 v99, v100, v99
	v_div_scale_f32 v100, vcc, v94, v98, v94
	v_mul_f32_e32 v101, v100, v99
	v_fma_f32 v102, -v95, v101, v100
	v_fmac_f32_e32 v101, v102, v99
	v_fma_f32 v95, -v95, v101, v100
	v_div_fmas_f32 v95, v95, v99, v101
	v_div_fixup_f32 v94, v95, v98, v94
	v_cvt_pk_bf16_f32 v94, v94, v2
	v_mul_f32_e32 v2, 0x3d372713, v96
	v_mul_f32_e32 v2, v96, v2
	v_fma_f32 v2, v96, v2, v96
	v_mul_f32_e32 v2, 0x3f4c422a, v2
	v_mul_f32_e32 v2, -2.0, v2
	v_mul_f32_e32 v2, 0x3fb8aa3b, v2
	v_exp_f32_e32 v98, v2
	v_mul_f32_e32 v2, 0x3d372713, v97
	v_mul_f32_e32 v2, v97, v2
	v_fma_f32 v2, v97, v2, v97
	v_mul_f32_e32 v2, 0x3f4c422a, v2
	v_mul_f32_e32 v2, -2.0, v2
	v_mul_f32_e32 v2, 0x3fb8aa3b, v2
	v_exp_f32_e32 v99, v2
	s_nop 0
	v_pk_add_f32 v[98:99], v[98:99], 1.0 op_sel_hi:[1,0]
	s_nop 0
	v_div_scale_f32 v2, s[8:9], v99, v99, v97
	v_rcp_f32_e32 v95, v2
	s_nop 0
	v_fma_f32 v100, -v2, v95, 1.0
	v_fmac_f32_e32 v95, v100, v95
	v_div_scale_f32 v100, vcc, v97, v99, v97
	v_mul_f32_e32 v101, v100, v95
	v_fma_f32 v102, -v2, v101, v100
	v_fmac_f32_e32 v101, v102, v95
	v_fma_f32 v2, -v2, v101, v100
	v_div_fmas_f32 v2, v2, v95, v101
	v_div_scale_f32 v95, s[8:9], v98, v98, v96
	v_div_fixup_f32 v2, v2, v99, v97
	v_rcp_f32_e32 v97, v95
	s_mov_b64 s[8:9], 0x12000
	v_fma_f32 v99, -v95, v97, 1.0
	v_fmac_f32_e32 v97, v99, v97
	v_div_scale_f32 v99, vcc, v96, v98, v96
	v_mul_f32_e32 v100, v99, v97
	v_fma_f32 v101, -v95, v100, v99
	v_fmac_f32_e32 v100, v101, v97
	v_fma_f32 v95, -v95, v100, v99
	v_div_fmas_f32 v95, v95, v97, v100
	v_div_fixup_f32 v95, v95, v98, v96
	v_add_co_u32_e32 v98, vcc, s1, v136
	v_cvt_pk_bf16_f32 v95, v95, v2
	s_nop 0
	v_addc_co_u32_e32 v99, vcc, 0, v137, vcc
	global_store_dwordx4 v[98:99], v[92:95], off
	v_lshl_add_u64 v[96:97], v[136:137], 0, s[8:9]
	s_mov_b32 s1, 0x14000
	v_pk_add_f32 v[92:93], v[80:81], v[88:89]
	v_pk_add_f32 v[80:81], v[78:79], v[86:87]
	v_mul_f32_e32 v2, 0x3d372713, v92
	v_mul_f32_e32 v2, v92, v2
	v_fma_f32 v2, v92, v2, v92
	v_mul_f32_e32 v2, 0x3f4c422a, v2
	v_mul_f32_e32 v2, -2.0, v2
	v_mul_f32_e32 v2, 0x3fb8aa3b, v2
	v_pk_add_f32 v[78:79], v[76:77], v[84:85]
	v_exp_f32_e32 v76, v2
	v_mul_f32_e32 v2, 0x3d372713, v93
	v_mul_f32_e32 v2, v93, v2
	v_fma_f32 v2, v93, v2, v93
	v_mul_f32_e32 v2, 0x3f4c422a, v2
	v_mul_f32_e32 v2, -2.0, v2
	v_mul_f32_e32 v2, 0x3fb8aa3b, v2
	v_exp_f32_e32 v77, v2
	s_nop 0
	v_pk_add_f32 v[76:77], v[76:77], 1.0 op_sel_hi:[1,0]
	s_nop 0
	v_div_scale_f32 v2, s[8:9], v77, v77, v93
	v_rcp_f32_e32 v94, v2
	s_nop 0
	v_fma_f32 v95, -v2, v94, 1.0
	v_fmac_f32_e32 v94, v95, v94
	v_div_scale_f32 v95, vcc, v93, v77, v93
	v_mul_f32_e32 v98, v95, v94
	v_fma_f32 v99, -v2, v98, v95
	v_fmac_f32_e32 v98, v99, v94
	v_fma_f32 v2, -v2, v98, v95
	v_div_fmas_f32 v2, v2, v94, v98
	v_div_fixup_f32 v2, v2, v77, v93
	v_div_scale_f32 v77, s[8:9], v76, v76, v92
	v_rcp_f32_e32 v93, v77
	s_nop 0
	v_fma_f32 v94, -v77, v93, 1.0
	v_fmac_f32_e32 v93, v94, v93
	v_div_scale_f32 v94, vcc, v92, v76, v92
	v_mul_f32_e32 v95, v94, v93
	v_fma_f32 v98, -v77, v95, v94
	v_fmac_f32_e32 v95, v98, v93
	v_fma_f32 v77, -v77, v95, v94
	v_div_fmas_f32 v77, v77, v93, v95
	v_div_fixup_f32 v76, v77, v76, v92
	v_cvt_pk_bf16_f32 v76, v76, v2
	v_mul_f32_e32 v2, 0x3d372713, v82
	v_mul_f32_e32 v2, v82, v2
	v_fma_f32 v2, v82, v2, v82
	v_mul_f32_e32 v2, 0x3f4c422a, v2
	v_mul_f32_e32 v2, -2.0, v2
	v_mul_f32_e32 v2, 0x3fb8aa3b, v2
	v_exp_f32_e32 v92, v2
	v_mul_f32_e32 v2, 0x3d372713, v83
	v_mul_f32_e32 v2, v83, v2
	v_fma_f32 v2, v83, v2, v83
	v_mul_f32_e32 v2, 0x3f4c422a, v2
	v_mul_f32_e32 v2, -2.0, v2
	v_mul_f32_e32 v2, 0x3fb8aa3b, v2
	v_exp_f32_e32 v93, v2
	s_nop 0
	v_pk_add_f32 v[92:93], v[92:93], 1.0 op_sel_hi:[1,0]
	s_nop 0
	v_div_scale_f32 v2, s[8:9], v93, v93, v83
	v_rcp_f32_e32 v77, v2
	s_nop 0
	v_fma_f32 v94, -v2, v77, 1.0
	v_fmac_f32_e32 v77, v94, v77
	v_div_scale_f32 v94, vcc, v83, v93, v83
	v_mul_f32_e32 v95, v94, v77
	v_fma_f32 v98, -v2, v95, v94
	v_fmac_f32_e32 v95, v98, v77
	v_fma_f32 v2, -v2, v95, v94
	v_div_fmas_f32 v2, v2, v77, v95
	v_div_scale_f32 v77, s[8:9], v92, v92, v82
	v_div_fixup_f32 v2, v2, v93, v83
	v_rcp_f32_e32 v83, v77
	s_nop 0
	v_fma_f32 v93, -v77, v83, 1.0
	v_fmac_f32_e32 v83, v93, v83
	v_div_scale_f32 v93, vcc, v82, v92, v82
	v_mul_f32_e32 v94, v93, v83
	v_fma_f32 v95, -v77, v94, v93
	v_fmac_f32_e32 v94, v95, v83
	v_fma_f32 v77, -v77, v94, v93
	v_div_fmas_f32 v77, v77, v83, v94
	v_div_fixup_f32 v77, v77, v92, v82
	v_cvt_pk_bf16_f32 v77, v77, v2
	v_mul_f32_e32 v2, 0x3d372713, v78
	v_mul_f32_e32 v2, v78, v2
	v_fma_f32 v2, v78, v2, v78
	v_mul_f32_e32 v2, 0x3f4c422a, v2
	v_mul_f32_e32 v2, -2.0, v2
	v_mul_f32_e32 v2, 0x3fb8aa3b, v2
	v_exp_f32_e32 v82, v2
	v_mul_f32_e32 v2, 0x3d372713, v79
	v_mul_f32_e32 v2, v79, v2
	v_fma_f32 v2, v79, v2, v79
	v_mul_f32_e32 v2, 0x3f4c422a, v2
	v_mul_f32_e32 v2, -2.0, v2
	v_mul_f32_e32 v2, 0x3fb8aa3b, v2
	v_exp_f32_e32 v83, v2
	s_nop 0
	v_pk_add_f32 v[82:83], v[82:83], 1.0 op_sel_hi:[1,0]
	s_nop 0
	v_div_scale_f32 v2, s[8:9], v83, v83, v79
	v_rcp_f32_e32 v92, v2
	s_nop 0
	v_fma_f32 v93, -v2, v92, 1.0
	v_fmac_f32_e32 v92, v93, v92
	v_div_scale_f32 v93, vcc, v79, v83, v79
	v_mul_f32_e32 v94, v93, v92
	v_fma_f32 v95, -v2, v94, v93
	v_fmac_f32_e32 v94, v95, v92
	v_fma_f32 v2, -v2, v94, v93
	v_div_fmas_f32 v2, v2, v92, v94
	v_div_fixup_f32 v2, v2, v83, v79
	v_div_scale_f32 v79, s[8:9], v82, v82, v78
	v_rcp_f32_e32 v83, v79
	s_nop 0
	v_fma_f32 v92, -v79, v83, 1.0
	v_fmac_f32_e32 v83, v92, v83
	v_div_scale_f32 v92, vcc, v78, v82, v78
	v_mul_f32_e32 v93, v92, v83
	v_fma_f32 v94, -v79, v93, v92
	v_fmac_f32_e32 v93, v94, v83
	v_fma_f32 v79, -v79, v93, v92
	v_div_fmas_f32 v79, v79, v83, v93
	v_div_fixup_f32 v78, v79, v82, v78
	v_cvt_pk_bf16_f32 v78, v78, v2
	v_mul_f32_e32 v2, 0x3d372713, v80
	v_mul_f32_e32 v2, v80, v2
	v_fma_f32 v2, v80, v2, v80
	v_mul_f32_e32 v2, 0x3f4c422a, v2
	v_mul_f32_e32 v2, -2.0, v2
	v_mul_f32_e32 v2, 0x3fb8aa3b, v2
	v_exp_f32_e32 v82, v2
	v_mul_f32_e32 v2, 0x3d372713, v81
	v_mul_f32_e32 v2, v81, v2
	v_fma_f32 v2, v81, v2, v81
	v_mul_f32_e32 v2, 0x3f4c422a, v2
	v_mul_f32_e32 v2, -2.0, v2
	v_mul_f32_e32 v2, 0x3fb8aa3b, v2
	v_exp_f32_e32 v83, v2
	s_nop 0
	v_pk_add_f32 v[82:83], v[82:83], 1.0 op_sel_hi:[1,0]
	s_nop 0
	v_div_scale_f32 v2, s[8:9], v83, v83, v81
	v_rcp_f32_e32 v79, v2
	s_nop 0
	v_fma_f32 v92, -v2, v79, 1.0
	v_fmac_f32_e32 v79, v92, v79
	v_div_scale_f32 v92, vcc, v81, v83, v81
	v_mul_f32_e32 v93, v92, v79
	v_fma_f32 v94, -v2, v93, v92
	v_fmac_f32_e32 v93, v94, v79
	v_fma_f32 v2, -v2, v93, v92
	v_div_fmas_f32 v2, v2, v79, v93
	v_div_scale_f32 v79, s[8:9], v82, v82, v80
	v_div_fixup_f32 v2, v2, v83, v81
	v_rcp_f32_e32 v81, v79
	s_mov_b64 s[8:9], 0x14000
	v_fma_f32 v83, -v79, v81, 1.0
	v_fmac_f32_e32 v81, v83, v81
	v_div_scale_f32 v83, vcc, v80, v82, v80
	v_mul_f32_e32 v92, v83, v81
	v_fma_f32 v93, -v79, v92, v83
	v_fmac_f32_e32 v92, v93, v81
	v_fma_f32 v79, -v79, v92, v83
	v_div_fmas_f32 v79, v79, v81, v92
	v_div_fixup_f32 v79, v79, v82, v80
	v_add_co_u32_e32 v82, vcc, s1, v136
	v_cvt_pk_bf16_f32 v79, v79, v2
	s_nop 0
	v_addc_co_u32_e32 v83, vcc, 0, v137, vcc
	global_store_dwordx4 v[82:83], v[76:79], off
	v_lshl_add_u64 v[80:81], v[136:137], 0, s[8:9]
	s_mov_b32 s1, 0x16000
	v_pk_add_f32 v[76:77], v[72:73], v[88:89]
	v_pk_add_f32 v[72:73], v[70:71], v[86:87]
	v_mul_f32_e32 v2, 0x3d372713, v76
	v_mul_f32_e32 v2, v76, v2
	v_fma_f32 v2, v76, v2, v76
	v_mul_f32_e32 v2, 0x3f4c422a, v2
	v_mul_f32_e32 v2, -2.0, v2
	v_mul_f32_e32 v2, 0x3fb8aa3b, v2
	v_pk_add_f32 v[70:71], v[68:69], v[84:85]
	v_exp_f32_e32 v68, v2
	v_mul_f32_e32 v2, 0x3d372713, v77
	v_mul_f32_e32 v2, v77, v2
	v_fma_f32 v2, v77, v2, v77
	v_mul_f32_e32 v2, 0x3f4c422a, v2
	v_mul_f32_e32 v2, -2.0, v2
	v_mul_f32_e32 v2, 0x3fb8aa3b, v2
	v_exp_f32_e32 v69, v2
	s_nop 0
	v_pk_add_f32 v[68:69], v[68:69], 1.0 op_sel_hi:[1,0]
	s_nop 0
	v_div_scale_f32 v2, s[8:9], v69, v69, v77
	v_rcp_f32_e32 v78, v2
	s_nop 0
	v_fma_f32 v79, -v2, v78, 1.0
	v_fmac_f32_e32 v78, v79, v78
	v_div_scale_f32 v79, vcc, v77, v69, v77
	v_mul_f32_e32 v82, v79, v78
	v_fma_f32 v83, -v2, v82, v79
	v_fmac_f32_e32 v82, v83, v78
	v_fma_f32 v2, -v2, v82, v79
	v_div_fmas_f32 v2, v2, v78, v82
	v_div_fixup_f32 v2, v2, v69, v77
	v_div_scale_f32 v69, s[8:9], v68, v68, v76
	v_rcp_f32_e32 v77, v69
	s_nop 0
	v_fma_f32 v78, -v69, v77, 1.0
	v_fmac_f32_e32 v77, v78, v77
	v_div_scale_f32 v78, vcc, v76, v68, v76
	v_mul_f32_e32 v79, v78, v77
	v_fma_f32 v82, -v69, v79, v78
	v_fmac_f32_e32 v79, v82, v77
	v_fma_f32 v69, -v69, v79, v78
	v_div_fmas_f32 v69, v69, v77, v79
	v_div_fixup_f32 v68, v69, v68, v76
	v_cvt_pk_bf16_f32 v68, v68, v2
	v_mul_f32_e32 v2, 0x3d372713, v74
	v_mul_f32_e32 v2, v74, v2
	v_fma_f32 v2, v74, v2, v74
	v_mul_f32_e32 v2, 0x3f4c422a, v2
	v_mul_f32_e32 v2, -2.0, v2
	v_mul_f32_e32 v2, 0x3fb8aa3b, v2
	v_exp_f32_e32 v76, v2
	v_mul_f32_e32 v2, 0x3d372713, v75
	v_mul_f32_e32 v2, v75, v2
	v_fma_f32 v2, v75, v2, v75
	v_mul_f32_e32 v2, 0x3f4c422a, v2
	v_mul_f32_e32 v2, -2.0, v2
	v_mul_f32_e32 v2, 0x3fb8aa3b, v2
	v_exp_f32_e32 v77, v2
	s_nop 0
	v_pk_add_f32 v[76:77], v[76:77], 1.0 op_sel_hi:[1,0]
	s_nop 0
	v_div_scale_f32 v2, s[8:9], v77, v77, v75
	v_rcp_f32_e32 v69, v2
	s_nop 0
	v_fma_f32 v78, -v2, v69, 1.0
	v_fmac_f32_e32 v69, v78, v69
	v_div_scale_f32 v78, vcc, v75, v77, v75
	v_mul_f32_e32 v79, v78, v69
	v_fma_f32 v82, -v2, v79, v78
	v_fmac_f32_e32 v79, v82, v69
	v_fma_f32 v2, -v2, v79, v78
	v_div_fmas_f32 v2, v2, v69, v79
	v_div_scale_f32 v69, s[8:9], v76, v76, v74
	v_div_fixup_f32 v2, v2, v77, v75
	v_rcp_f32_e32 v75, v69
	s_nop 0
	v_fma_f32 v77, -v69, v75, 1.0
	v_fmac_f32_e32 v75, v77, v75
	v_div_scale_f32 v77, vcc, v74, v76, v74
	v_mul_f32_e32 v78, v77, v75
	v_fma_f32 v79, -v69, v78, v77
	v_fmac_f32_e32 v78, v79, v75
	v_fma_f32 v69, -v69, v78, v77
	v_div_fmas_f32 v69, v69, v75, v78
	v_div_fixup_f32 v69, v69, v76, v74
	v_cvt_pk_bf16_f32 v69, v69, v2
	v_mul_f32_e32 v2, 0x3d372713, v70
	v_mul_f32_e32 v2, v70, v2
	v_fma_f32 v2, v70, v2, v70
	v_mul_f32_e32 v2, 0x3f4c422a, v2
	v_mul_f32_e32 v2, -2.0, v2
	v_mul_f32_e32 v2, 0x3fb8aa3b, v2
	v_exp_f32_e32 v74, v2
	v_mul_f32_e32 v2, 0x3d372713, v71
	v_mul_f32_e32 v2, v71, v2
	v_fma_f32 v2, v71, v2, v71
	v_mul_f32_e32 v2, 0x3f4c422a, v2
	v_mul_f32_e32 v2, -2.0, v2
	v_mul_f32_e32 v2, 0x3fb8aa3b, v2
	v_exp_f32_e32 v75, v2
	s_nop 0
	v_pk_add_f32 v[74:75], v[74:75], 1.0 op_sel_hi:[1,0]
	s_nop 0
	v_div_scale_f32 v2, s[8:9], v75, v75, v71
	v_rcp_f32_e32 v76, v2
	s_nop 0
	v_fma_f32 v77, -v2, v76, 1.0
	v_fmac_f32_e32 v76, v77, v76
	v_div_scale_f32 v77, vcc, v71, v75, v71
	v_mul_f32_e32 v78, v77, v76
	v_fma_f32 v79, -v2, v78, v77
	v_fmac_f32_e32 v78, v79, v76
	v_fma_f32 v2, -v2, v78, v77
	v_div_fmas_f32 v2, v2, v76, v78
	v_div_fixup_f32 v2, v2, v75, v71
	v_div_scale_f32 v71, s[8:9], v74, v74, v70
	v_rcp_f32_e32 v75, v71
	s_nop 0
	v_fma_f32 v76, -v71, v75, 1.0
	v_fmac_f32_e32 v75, v76, v75
	v_div_scale_f32 v76, vcc, v70, v74, v70
	v_mul_f32_e32 v77, v76, v75
	v_fma_f32 v78, -v71, v77, v76
	v_fmac_f32_e32 v77, v78, v75
	v_fma_f32 v71, -v71, v77, v76
	v_div_fmas_f32 v71, v71, v75, v77
	v_div_fixup_f32 v70, v71, v74, v70
	v_cvt_pk_bf16_f32 v70, v70, v2
	v_mul_f32_e32 v2, 0x3d372713, v72
	v_mul_f32_e32 v2, v72, v2
	v_fma_f32 v2, v72, v2, v72
	v_mul_f32_e32 v2, 0x3f4c422a, v2
	v_mul_f32_e32 v2, -2.0, v2
	v_mul_f32_e32 v2, 0x3fb8aa3b, v2
	v_exp_f32_e32 v74, v2
	v_mul_f32_e32 v2, 0x3d372713, v73
	v_mul_f32_e32 v2, v73, v2
	v_fma_f32 v2, v73, v2, v73
	v_mul_f32_e32 v2, 0x3f4c422a, v2
	v_mul_f32_e32 v2, -2.0, v2
	v_mul_f32_e32 v2, 0x3fb8aa3b, v2
	v_exp_f32_e32 v75, v2
	s_nop 0
	v_pk_add_f32 v[74:75], v[74:75], 1.0 op_sel_hi:[1,0]
	s_nop 0
	v_div_scale_f32 v2, s[8:9], v75, v75, v73
	v_rcp_f32_e32 v71, v2
	s_nop 0
	v_fma_f32 v76, -v2, v71, 1.0
	v_fmac_f32_e32 v71, v76, v71
	v_div_scale_f32 v76, vcc, v73, v75, v73
	v_mul_f32_e32 v77, v76, v71
	v_fma_f32 v78, -v2, v77, v76
	v_fmac_f32_e32 v77, v78, v71
	v_fma_f32 v2, -v2, v77, v76
	v_div_fmas_f32 v2, v2, v71, v77
	v_div_scale_f32 v71, s[8:9], v74, v74, v72
	v_div_fixup_f32 v2, v2, v75, v73
	v_rcp_f32_e32 v73, v71
	s_mov_b64 s[8:9], 0x16000
	v_fma_f32 v75, -v71, v73, 1.0
	v_fmac_f32_e32 v73, v75, v73
	v_div_scale_f32 v75, vcc, v72, v74, v72
	v_mul_f32_e32 v76, v75, v73
	v_fma_f32 v77, -v71, v76, v75
	v_fmac_f32_e32 v76, v77, v73
	v_fma_f32 v71, -v71, v76, v75
	v_div_fmas_f32 v71, v71, v73, v76
	v_div_fixup_f32 v71, v71, v74, v72
	v_add_co_u32_e32 v72, vcc, s1, v136
	v_cvt_pk_bf16_f32 v71, v71, v2
	s_nop 0
	v_addc_co_u32_e32 v73, vcc, 0, v137, vcc
	global_store_dwordx4 v[72:73], v[68:71], off
	global_load_dwordx4 v[68:71], v[152:153], off offset:528
	s_nop 0
	global_load_dwordx4 v[72:75], v[152:153], off offset:512
	v_lshl_add_u64 v[76:77], v[136:137], 0, s[8:9]
	s_waitcnt vmcnt(0)
	v_pk_add_f32 v[78:79], v[64:65], v[72:73]
	s_nop 0
	v_mul_f32_e32 v2, 0x3d372713, v78
	v_mul_f32_e32 v2, v78, v2
	v_fma_f32 v2, v78, v2, v78
	v_mul_f32_e32 v2, 0x3f4c422a, v2
	v_mul_f32_e32 v2, -2.0, v2
	v_mul_f32_e32 v2, 0x3fb8aa3b, v2
	v_pk_add_f32 v[64:65], v[62:63], v[70:71]
	v_pk_add_f32 v[62:63], v[60:61], v[68:69]
	v_exp_f32_e32 v60, v2
	v_mul_f32_e32 v2, 0x3d372713, v79
	v_mul_f32_e32 v2, v79, v2
	v_fma_f32 v2, v79, v2, v79
	v_mul_f32_e32 v2, 0x3f4c422a, v2
	v_mul_f32_e32 v2, -2.0, v2
	v_mul_f32_e32 v2, 0x3fb8aa3b, v2
	v_exp_f32_e32 v61, v2
	v_pk_add_f32 v[66:67], v[66:67], v[74:75]
	v_pk_add_f32 v[58:59], v[58:59], v[74:75]
	v_pk_add_f32 v[50:51], v[50:51], v[74:75]
	v_pk_add_f32 v[60:61], v[60:61], 1.0 op_sel_hi:[1,0]
	v_pk_add_f32 v[42:43], v[42:43], v[74:75]
	v_div_scale_f32 v2, s[8:9], v61, v61, v79
	v_rcp_f32_e32 v82, v2
	v_pk_add_f32 v[34:35], v[34:35], v[74:75]
	v_pk_add_f32 v[26:27], v[26:27], v[74:75]
	v_pk_add_f32 v[18:19], v[18:19], v[74:75]
	v_fma_f32 v83, -v2, v82, 1.0
	v_fmac_f32_e32 v82, v83, v82
	v_div_scale_f32 v83, vcc, v79, v61, v79
	v_mul_f32_e32 v84, v83, v82
	v_fma_f32 v85, -v2, v84, v83
	v_fmac_f32_e32 v84, v85, v82
	v_fma_f32 v2, -v2, v84, v83
	v_div_fmas_f32 v2, v2, v82, v84
	v_div_fixup_f32 v2, v2, v61, v79
	v_div_scale_f32 v61, s[8:9], v60, v60, v78
	v_rcp_f32_e32 v79, v61
	v_pk_add_f32 v[10:11], v[10:11], v[74:75]
	v_fma_f32 v82, -v61, v79, 1.0
	v_fmac_f32_e32 v79, v82, v79
	v_div_scale_f32 v82, vcc, v78, v60, v78
	v_mul_f32_e32 v83, v82, v79
	v_fma_f32 v84, -v61, v83, v82
	v_fmac_f32_e32 v83, v84, v79
	v_fma_f32 v61, -v61, v83, v82
	v_div_fmas_f32 v61, v61, v79, v83
	v_div_fixup_f32 v60, v61, v60, v78
	v_cvt_pk_bf16_f32 v60, v60, v2
	v_mul_f32_e32 v2, 0x3d372713, v66
	v_mul_f32_e32 v2, v66, v2
	v_fma_f32 v2, v66, v2, v66
	v_mul_f32_e32 v2, 0x3f4c422a, v2
	v_mul_f32_e32 v2, -2.0, v2
	v_mul_f32_e32 v2, 0x3fb8aa3b, v2
	v_exp_f32_e32 v78, v2
	v_mul_f32_e32 v2, 0x3d372713, v67
	v_mul_f32_e32 v2, v67, v2
	v_fma_f32 v2, v67, v2, v67
	v_mul_f32_e32 v2, 0x3f4c422a, v2
	v_mul_f32_e32 v2, -2.0, v2
	v_mul_f32_e32 v2, 0x3fb8aa3b, v2
	v_exp_f32_e32 v79, v2
	s_nop 0
	v_pk_add_f32 v[78:79], v[78:79], 1.0 op_sel_hi:[1,0]
	s_nop 0
	v_div_scale_f32 v2, s[8:9], v79, v79, v67
	v_rcp_f32_e32 v61, v2
	s_nop 0
	v_fma_f32 v82, -v2, v61, 1.0
	v_fmac_f32_e32 v61, v82, v61
	v_div_scale_f32 v82, vcc, v67, v79, v67
	v_mul_f32_e32 v83, v82, v61
	v_fma_f32 v84, -v2, v83, v82
	v_fmac_f32_e32 v83, v84, v61
	v_fma_f32 v2, -v2, v83, v82
	v_div_fmas_f32 v2, v2, v61, v83
	v_div_scale_f32 v61, s[8:9], v78, v78, v66
	v_div_fixup_f32 v2, v2, v79, v67
	v_rcp_f32_e32 v67, v61
	s_nop 0
	v_fma_f32 v79, -v61, v67, 1.0
	v_fmac_f32_e32 v67, v79, v67
	v_div_scale_f32 v79, vcc, v66, v78, v66
	v_mul_f32_e32 v82, v79, v67
	v_fma_f32 v83, -v61, v82, v79
	v_fmac_f32_e32 v82, v83, v67
	v_fma_f32 v61, -v61, v82, v79
	v_div_fmas_f32 v61, v61, v67, v82
	v_div_fixup_f32 v61, v61, v78, v66
	v_cvt_pk_bf16_f32 v61, v61, v2
	v_mul_f32_e32 v2, 0x3d372713, v62
	v_mul_f32_e32 v2, v62, v2
	v_fma_f32 v2, v62, v2, v62
	v_mul_f32_e32 v2, 0x3f4c422a, v2
	v_mul_f32_e32 v2, -2.0, v2
	v_mul_f32_e32 v2, 0x3fb8aa3b, v2
	v_exp_f32_e32 v66, v2
	v_mul_f32_e32 v2, 0x3d372713, v63
	v_mul_f32_e32 v2, v63, v2
	v_fma_f32 v2, v63, v2, v63
	v_mul_f32_e32 v2, 0x3f4c422a, v2
	v_mul_f32_e32 v2, -2.0, v2
	v_mul_f32_e32 v2, 0x3fb8aa3b, v2
	v_exp_f32_e32 v67, v2
	s_nop 0
	v_pk_add_f32 v[66:67], v[66:67], 1.0 op_sel_hi:[1,0]
	s_nop 0
	v_div_scale_f32 v2, s[8:9], v67, v67, v63
	v_rcp_f32_e32 v78, v2
	s_nop 0
	v_fma_f32 v79, -v2, v78, 1.0
	v_fmac_f32_e32 v78, v79, v78
	v_div_scale_f32 v79, vcc, v63, v67, v63
	v_mul_f32_e32 v82, v79, v78
	v_fma_f32 v83, -v2, v82, v79
	v_fmac_f32_e32 v82, v83, v78
	v_fma_f32 v2, -v2, v82, v79
	v_div_fmas_f32 v2, v2, v78, v82
	v_div_fixup_f32 v2, v2, v67, v63
	v_div_scale_f32 v63, s[8:9], v66, v66, v62
	v_rcp_f32_e32 v67, v63
	s_nop 0
	v_fma_f32 v78, -v63, v67, 1.0
	v_fmac_f32_e32 v67, v78, v67
	v_div_scale_f32 v78, vcc, v62, v66, v62
	v_mul_f32_e32 v79, v78, v67
	v_fma_f32 v82, -v63, v79, v78
	v_fmac_f32_e32 v79, v82, v67
	v_fma_f32 v63, -v63, v79, v78
	v_div_fmas_f32 v63, v63, v67, v79
	v_div_fixup_f32 v62, v63, v66, v62
	v_cvt_pk_bf16_f32 v62, v62, v2
	v_mul_f32_e32 v2, 0x3d372713, v64
	v_mul_f32_e32 v2, v64, v2
	v_fma_f32 v2, v64, v2, v64
	v_mul_f32_e32 v2, 0x3f4c422a, v2
	v_mul_f32_e32 v2, -2.0, v2
	v_mul_f32_e32 v2, 0x3fb8aa3b, v2
	v_exp_f32_e32 v66, v2
	v_mul_f32_e32 v2, 0x3d372713, v65
	v_mul_f32_e32 v2, v65, v2
	v_fma_f32 v2, v65, v2, v65
	v_mul_f32_e32 v2, 0x3f4c422a, v2
	v_mul_f32_e32 v2, -2.0, v2
	v_mul_f32_e32 v2, 0x3fb8aa3b, v2
	v_exp_f32_e32 v67, v2
	s_nop 0
	v_pk_add_f32 v[66:67], v[66:67], 1.0 op_sel_hi:[1,0]
	s_nop 0
	v_div_scale_f32 v2, s[8:9], v67, v67, v65
	v_rcp_f32_e32 v63, v2
	s_nop 0
	v_fma_f32 v78, -v2, v63, 1.0
	v_fmac_f32_e32 v63, v78, v63
	v_div_scale_f32 v78, vcc, v65, v67, v65
	v_mul_f32_e32 v79, v78, v63
	v_fma_f32 v82, -v2, v79, v78
	v_fmac_f32_e32 v79, v82, v63
	v_fma_f32 v2, -v2, v79, v78
	v_div_fmas_f32 v2, v2, v63, v79
	v_div_scale_f32 v63, s[8:9], v66, v66, v64
	v_div_fixup_f32 v2, v2, v67, v65
	v_rcp_f32_e32 v65, v63
	s_nop 0
	v_fma_f32 v67, -v63, v65, 1.0
	v_fmac_f32_e32 v65, v67, v65
	v_div_scale_f32 v67, vcc, v64, v66, v64
	v_mul_f32_e32 v78, v67, v65
	v_fma_f32 v79, -v63, v78, v67
	v_fmac_f32_e32 v78, v79, v65
	v_fma_f32 v63, -v63, v78, v67
	v_div_fmas_f32 v63, v63, v65, v78
	v_div_fixup_f32 v63, v63, v66, v64
	v_cvt_pk_bf16_f32 v63, v63, v2
	global_store_dwordx4 v[136:137], v[60:63], off offset:256
	s_nop 1
	v_pk_add_f32 v[60:61], v[56:57], v[72:73]
	v_pk_add_f32 v[56:57], v[54:55], v[70:71]
	v_mul_f32_e32 v2, 0x3d372713, v60
	v_mul_f32_e32 v2, v60, v2
	v_fma_f32 v2, v60, v2, v60
	v_mul_f32_e32 v2, 0x3f4c422a, v2
	v_mul_f32_e32 v2, -2.0, v2
	v_mul_f32_e32 v2, 0x3fb8aa3b, v2
	v_pk_add_f32 v[54:55], v[52:53], v[68:69]
	v_exp_f32_e32 v52, v2
	v_mul_f32_e32 v2, 0x3d372713, v61
	v_mul_f32_e32 v2, v61, v2
	v_fma_f32 v2, v61, v2, v61
	v_mul_f32_e32 v2, 0x3f4c422a, v2
	v_mul_f32_e32 v2, -2.0, v2
	v_mul_f32_e32 v2, 0x3fb8aa3b, v2
	v_exp_f32_e32 v53, v2
	s_nop 0
	v_pk_add_f32 v[52:53], v[52:53], 1.0 op_sel_hi:[1,0]
	s_nop 0
	v_div_scale_f32 v2, s[8:9], v53, v53, v61
	v_rcp_f32_e32 v62, v2
	s_nop 0
	v_fma_f32 v63, -v2, v62, 1.0
	v_fmac_f32_e32 v62, v63, v62
	v_div_scale_f32 v63, vcc, v61, v53, v61
	v_mul_f32_e32 v64, v63, v62
	v_fma_f32 v65, -v2, v64, v63
	v_fmac_f32_e32 v64, v65, v62
	v_fma_f32 v2, -v2, v64, v63
	v_div_fmas_f32 v2, v2, v62, v64
	v_div_fixup_f32 v2, v2, v53, v61
	v_div_scale_f32 v53, s[8:9], v52, v52, v60
	v_rcp_f32_e32 v61, v53
	s_nop 0
	v_fma_f32 v62, -v53, v61, 1.0
	v_fmac_f32_e32 v61, v62, v61
	v_div_scale_f32 v62, vcc, v60, v52, v60
	v_mul_f32_e32 v63, v62, v61
	v_fma_f32 v64, -v53, v63, v62
	v_fmac_f32_e32 v63, v64, v61
	v_fma_f32 v53, -v53, v63, v62
	v_div_fmas_f32 v53, v53, v61, v63
	v_div_fixup_f32 v52, v53, v52, v60
	v_cvt_pk_bf16_f32 v52, v52, v2
	v_mul_f32_e32 v2, 0x3d372713, v58
	v_mul_f32_e32 v2, v58, v2
	v_fma_f32 v2, v58, v2, v58
	v_mul_f32_e32 v2, 0x3f4c422a, v2
	v_mul_f32_e32 v2, -2.0, v2
	v_mul_f32_e32 v2, 0x3fb8aa3b, v2
	v_exp_f32_e32 v60, v2
	v_mul_f32_e32 v2, 0x3d372713, v59
	v_mul_f32_e32 v2, v59, v2
	v_fma_f32 v2, v59, v2, v59
	v_mul_f32_e32 v2, 0x3f4c422a, v2
	v_mul_f32_e32 v2, -2.0, v2
	v_mul_f32_e32 v2, 0x3fb8aa3b, v2
	v_exp_f32_e32 v61, v2
	s_nop 0
	v_pk_add_f32 v[60:61], v[60:61], 1.0 op_sel_hi:[1,0]
	s_nop 0
	v_div_scale_f32 v2, s[8:9], v61, v61, v59
	v_rcp_f32_e32 v53, v2
	s_nop 0
	v_fma_f32 v62, -v2, v53, 1.0
	v_fmac_f32_e32 v53, v62, v53
	v_div_scale_f32 v62, vcc, v59, v61, v59
	v_mul_f32_e32 v63, v62, v53
	v_fma_f32 v64, -v2, v63, v62
	v_fmac_f32_e32 v63, v64, v53
	v_fma_f32 v2, -v2, v63, v62
	v_div_fmas_f32 v2, v2, v53, v63
	v_div_scale_f32 v53, s[8:9], v60, v60, v58
	v_div_fixup_f32 v2, v2, v61, v59
	v_rcp_f32_e32 v59, v53
	s_nop 0
	v_fma_f32 v61, -v53, v59, 1.0
	v_fmac_f32_e32 v59, v61, v59
	v_div_scale_f32 v61, vcc, v58, v60, v58
	v_mul_f32_e32 v62, v61, v59
	v_fma_f32 v63, -v53, v62, v61
	v_fmac_f32_e32 v62, v63, v59
	v_fma_f32 v53, -v53, v62, v61
	v_div_fmas_f32 v53, v53, v59, v62
	v_div_fixup_f32 v53, v53, v60, v58
	v_cvt_pk_bf16_f32 v53, v53, v2
	v_mul_f32_e32 v2, 0x3d372713, v54
	v_mul_f32_e32 v2, v54, v2
	v_fma_f32 v2, v54, v2, v54
	v_mul_f32_e32 v2, 0x3f4c422a, v2
	v_mul_f32_e32 v2, -2.0, v2
	v_mul_f32_e32 v2, 0x3fb8aa3b, v2
	v_exp_f32_e32 v58, v2
	v_mul_f32_e32 v2, 0x3d372713, v55
	v_mul_f32_e32 v2, v55, v2
	v_fma_f32 v2, v55, v2, v55
	v_mul_f32_e32 v2, 0x3f4c422a, v2
	v_mul_f32_e32 v2, -2.0, v2
	v_mul_f32_e32 v2, 0x3fb8aa3b, v2
	v_exp_f32_e32 v59, v2
	s_nop 0
	v_pk_add_f32 v[58:59], v[58:59], 1.0 op_sel_hi:[1,0]
	s_nop 0
	v_div_scale_f32 v2, s[8:9], v59, v59, v55
	v_rcp_f32_e32 v60, v2
	s_nop 0
	v_fma_f32 v61, -v2, v60, 1.0
	v_fmac_f32_e32 v60, v61, v60
	v_div_scale_f32 v61, vcc, v55, v59, v55
	v_mul_f32_e32 v62, v61, v60
	v_fma_f32 v63, -v2, v62, v61
	v_fmac_f32_e32 v62, v63, v60
	v_fma_f32 v2, -v2, v62, v61
	v_div_fmas_f32 v2, v2, v60, v62
	v_div_fixup_f32 v2, v2, v59, v55
	v_div_scale_f32 v55, s[8:9], v58, v58, v54
	v_rcp_f32_e32 v59, v55
	s_nop 0
	v_fma_f32 v60, -v55, v59, 1.0
	v_fmac_f32_e32 v59, v60, v59
	v_div_scale_f32 v60, vcc, v54, v58, v54
	v_mul_f32_e32 v61, v60, v59
	v_fma_f32 v62, -v55, v61, v60
	v_fmac_f32_e32 v61, v62, v59
	v_fma_f32 v55, -v55, v61, v60
	v_div_fmas_f32 v55, v55, v59, v61
	v_div_fixup_f32 v54, v55, v58, v54
	v_cvt_pk_bf16_f32 v54, v54, v2
	v_mul_f32_e32 v2, 0x3d372713, v56
	v_mul_f32_e32 v2, v56, v2
	v_fma_f32 v2, v56, v2, v56
	v_mul_f32_e32 v2, 0x3f4c422a, v2
	v_mul_f32_e32 v2, -2.0, v2
	v_mul_f32_e32 v2, 0x3fb8aa3b, v2
	v_exp_f32_e32 v58, v2
	v_mul_f32_e32 v2, 0x3d372713, v57
	v_mul_f32_e32 v2, v57, v2
	v_fma_f32 v2, v57, v2, v57
	v_mul_f32_e32 v2, 0x3f4c422a, v2
	v_mul_f32_e32 v2, -2.0, v2
	v_mul_f32_e32 v2, 0x3fb8aa3b, v2
	v_exp_f32_e32 v59, v2
	s_nop 0
	v_pk_add_f32 v[58:59], v[58:59], 1.0 op_sel_hi:[1,0]
	s_nop 0
	v_div_scale_f32 v2, s[8:9], v59, v59, v57
	v_rcp_f32_e32 v55, v2
	s_nop 0
	v_fma_f32 v60, -v2, v55, 1.0
	v_fmac_f32_e32 v55, v60, v55
	v_div_scale_f32 v60, vcc, v57, v59, v57
	v_mul_f32_e32 v61, v60, v55
	v_fma_f32 v62, -v2, v61, v60
	v_fmac_f32_e32 v61, v62, v55
	v_fma_f32 v2, -v2, v61, v60
	v_div_fmas_f32 v2, v2, v55, v61
	v_div_scale_f32 v55, s[8:9], v58, v58, v56
	v_div_fixup_f32 v2, v2, v59, v57
	v_rcp_f32_e32 v57, v55
	s_nop 0
	v_fma_f32 v59, -v55, v57, 1.0
	v_fmac_f32_e32 v57, v59, v57
	v_div_scale_f32 v59, vcc, v56, v58, v56
	v_mul_f32_e32 v60, v59, v57
	v_fma_f32 v61, -v55, v60, v59
	v_fmac_f32_e32 v60, v61, v57
	v_fma_f32 v55, -v55, v60, v59
	v_div_fmas_f32 v55, v55, v57, v60
	v_div_fixup_f32 v55, v55, v58, v56
	v_cvt_pk_bf16_f32 v55, v55, v2
	global_store_dwordx4 v[128:129], v[52:55], off offset:256
	s_nop 1
	v_pk_add_f32 v[52:53], v[48:49], v[72:73]
	v_pk_add_f32 v[48:49], v[46:47], v[70:71]
	v_mul_f32_e32 v2, 0x3d372713, v52
	v_mul_f32_e32 v2, v52, v2
	v_fma_f32 v2, v52, v2, v52
	v_mul_f32_e32 v2, 0x3f4c422a, v2
	v_mul_f32_e32 v2, -2.0, v2
	v_mul_f32_e32 v2, 0x3fb8aa3b, v2
	v_pk_add_f32 v[46:47], v[44:45], v[68:69]
	v_exp_f32_e32 v44, v2
	v_mul_f32_e32 v2, 0x3d372713, v53
	v_mul_f32_e32 v2, v53, v2
	v_fma_f32 v2, v53, v2, v53
	v_mul_f32_e32 v2, 0x3f4c422a, v2
	v_mul_f32_e32 v2, -2.0, v2
	v_mul_f32_e32 v2, 0x3fb8aa3b, v2
	v_exp_f32_e32 v45, v2
	s_nop 0
	v_pk_add_f32 v[44:45], v[44:45], 1.0 op_sel_hi:[1,0]
	s_nop 0
	v_div_scale_f32 v2, s[8:9], v45, v45, v53
	v_rcp_f32_e32 v54, v2
	s_nop 0
	v_fma_f32 v55, -v2, v54, 1.0
	v_fmac_f32_e32 v54, v55, v54
	v_div_scale_f32 v55, vcc, v53, v45, v53
	v_mul_f32_e32 v56, v55, v54
	v_fma_f32 v57, -v2, v56, v55
	v_fmac_f32_e32 v56, v57, v54
	v_fma_f32 v2, -v2, v56, v55
	v_div_fmas_f32 v2, v2, v54, v56
	v_div_fixup_f32 v2, v2, v45, v53
	v_div_scale_f32 v45, s[8:9], v44, v44, v52
	v_rcp_f32_e32 v53, v45
	s_nop 0
	v_fma_f32 v54, -v45, v53, 1.0
	v_fmac_f32_e32 v53, v54, v53
	v_div_scale_f32 v54, vcc, v52, v44, v52
	v_mul_f32_e32 v55, v54, v53
	v_fma_f32 v56, -v45, v55, v54
	v_fmac_f32_e32 v55, v56, v53
	v_fma_f32 v45, -v45, v55, v54
	v_div_fmas_f32 v45, v45, v53, v55
	v_div_fixup_f32 v44, v45, v44, v52
	v_cvt_pk_bf16_f32 v44, v44, v2
	v_mul_f32_e32 v2, 0x3d372713, v50
	v_mul_f32_e32 v2, v50, v2
	v_fma_f32 v2, v50, v2, v50
	v_mul_f32_e32 v2, 0x3f4c422a, v2
	v_mul_f32_e32 v2, -2.0, v2
	v_mul_f32_e32 v2, 0x3fb8aa3b, v2
	v_exp_f32_e32 v52, v2
	v_mul_f32_e32 v2, 0x3d372713, v51
	v_mul_f32_e32 v2, v51, v2
	v_fma_f32 v2, v51, v2, v51
	v_mul_f32_e32 v2, 0x3f4c422a, v2
	v_mul_f32_e32 v2, -2.0, v2
	v_mul_f32_e32 v2, 0x3fb8aa3b, v2
	v_exp_f32_e32 v53, v2
	s_nop 0
	v_pk_add_f32 v[52:53], v[52:53], 1.0 op_sel_hi:[1,0]
	s_nop 0
	v_div_scale_f32 v2, s[8:9], v53, v53, v51
	v_rcp_f32_e32 v45, v2
	s_nop 0
	v_fma_f32 v54, -v2, v45, 1.0
	v_fmac_f32_e32 v45, v54, v45
	v_div_scale_f32 v54, vcc, v51, v53, v51
	v_mul_f32_e32 v55, v54, v45
	v_fma_f32 v56, -v2, v55, v54
	v_fmac_f32_e32 v55, v56, v45
	v_fma_f32 v2, -v2, v55, v54
	v_div_fmas_f32 v2, v2, v45, v55
	v_div_scale_f32 v45, s[8:9], v52, v52, v50
	v_div_fixup_f32 v2, v2, v53, v51
	v_rcp_f32_e32 v51, v45
	s_nop 0
	v_fma_f32 v53, -v45, v51, 1.0
	v_fmac_f32_e32 v51, v53, v51
	v_div_scale_f32 v53, vcc, v50, v52, v50
	v_mul_f32_e32 v54, v53, v51
	v_fma_f32 v55, -v45, v54, v53
	v_fmac_f32_e32 v54, v55, v51
	v_fma_f32 v45, -v45, v54, v53
	v_div_fmas_f32 v45, v45, v51, v54
	v_div_fixup_f32 v45, v45, v52, v50
	v_cvt_pk_bf16_f32 v45, v45, v2
	v_mul_f32_e32 v2, 0x3d372713, v46
	v_mul_f32_e32 v2, v46, v2
	v_fma_f32 v2, v46, v2, v46
	v_mul_f32_e32 v2, 0x3f4c422a, v2
	v_mul_f32_e32 v2, -2.0, v2
	v_mul_f32_e32 v2, 0x3fb8aa3b, v2
	v_exp_f32_e32 v50, v2
	v_mul_f32_e32 v2, 0x3d372713, v47
	v_mul_f32_e32 v2, v47, v2
	v_fma_f32 v2, v47, v2, v47
	v_mul_f32_e32 v2, 0x3f4c422a, v2
	v_mul_f32_e32 v2, -2.0, v2
	v_mul_f32_e32 v2, 0x3fb8aa3b, v2
	v_exp_f32_e32 v51, v2
	s_nop 0
	v_pk_add_f32 v[50:51], v[50:51], 1.0 op_sel_hi:[1,0]
	s_nop 0
	v_div_scale_f32 v2, s[8:9], v51, v51, v47
	v_rcp_f32_e32 v52, v2
	s_nop 0
	v_fma_f32 v53, -v2, v52, 1.0
	v_fmac_f32_e32 v52, v53, v52
	v_div_scale_f32 v53, vcc, v47, v51, v47
	v_mul_f32_e32 v54, v53, v52
	v_fma_f32 v55, -v2, v54, v53
	v_fmac_f32_e32 v54, v55, v52
	v_fma_f32 v2, -v2, v54, v53
	v_div_fmas_f32 v2, v2, v52, v54
	v_div_fixup_f32 v2, v2, v51, v47
	v_div_scale_f32 v47, s[8:9], v50, v50, v46
	v_rcp_f32_e32 v51, v47
	s_nop 0
	v_fma_f32 v52, -v47, v51, 1.0
	v_fmac_f32_e32 v51, v52, v51
	v_div_scale_f32 v52, vcc, v46, v50, v46
	v_mul_f32_e32 v53, v52, v51
	v_fma_f32 v54, -v47, v53, v52
	v_fmac_f32_e32 v53, v54, v51
	v_fma_f32 v47, -v47, v53, v52
	v_div_fmas_f32 v47, v47, v51, v53
	v_div_fixup_f32 v46, v47, v50, v46
	v_cvt_pk_bf16_f32 v46, v46, v2
	v_mul_f32_e32 v2, 0x3d372713, v48
	v_mul_f32_e32 v2, v48, v2
	v_fma_f32 v2, v48, v2, v48
	v_mul_f32_e32 v2, 0x3f4c422a, v2
	v_mul_f32_e32 v2, -2.0, v2
	v_mul_f32_e32 v2, 0x3fb8aa3b, v2
	v_exp_f32_e32 v50, v2
	v_mul_f32_e32 v2, 0x3d372713, v49
	v_mul_f32_e32 v2, v49, v2
	v_fma_f32 v2, v49, v2, v49
	v_mul_f32_e32 v2, 0x3f4c422a, v2
	v_mul_f32_e32 v2, -2.0, v2
	v_mul_f32_e32 v2, 0x3fb8aa3b, v2
	v_exp_f32_e32 v51, v2
	s_nop 0
	v_pk_add_f32 v[50:51], v[50:51], 1.0 op_sel_hi:[1,0]
	s_nop 0
	v_div_scale_f32 v2, s[8:9], v51, v51, v49
	v_rcp_f32_e32 v47, v2
	s_nop 0
	v_fma_f32 v52, -v2, v47, 1.0
	v_fmac_f32_e32 v47, v52, v47
	v_div_scale_f32 v52, vcc, v49, v51, v49
	v_mul_f32_e32 v53, v52, v47
	v_fma_f32 v54, -v2, v53, v52
	v_fmac_f32_e32 v53, v54, v47
	v_fma_f32 v2, -v2, v53, v52
	v_div_fmas_f32 v2, v2, v47, v53
	v_div_scale_f32 v47, s[8:9], v50, v50, v48
	v_div_fixup_f32 v2, v2, v51, v49
	v_rcp_f32_e32 v49, v47
	s_nop 0
	v_fma_f32 v51, -v47, v49, 1.0
	v_fmac_f32_e32 v49, v51, v49
	v_div_scale_f32 v51, vcc, v48, v50, v48
	v_mul_f32_e32 v52, v51, v49
	v_fma_f32 v53, -v47, v52, v51
	v_fmac_f32_e32 v52, v53, v49
	v_fma_f32 v47, -v47, v52, v51
	v_div_fmas_f32 v47, v47, v49, v52
	v_div_fixup_f32 v47, v47, v50, v48
	v_cvt_pk_bf16_f32 v47, v47, v2
	global_store_dwordx4 v[120:121], v[44:47], off offset:256
	s_nop 1
	v_pk_add_f32 v[44:45], v[40:41], v[72:73]
	v_pk_add_f32 v[40:41], v[38:39], v[70:71]
	v_mul_f32_e32 v2, 0x3d372713, v44
	v_mul_f32_e32 v2, v44, v2
	v_fma_f32 v2, v44, v2, v44
	v_mul_f32_e32 v2, 0x3f4c422a, v2
	v_mul_f32_e32 v2, -2.0, v2
	v_mul_f32_e32 v2, 0x3fb8aa3b, v2
	v_pk_add_f32 v[38:39], v[36:37], v[68:69]
	v_exp_f32_e32 v36, v2
	v_mul_f32_e32 v2, 0x3d372713, v45
	v_mul_f32_e32 v2, v45, v2
	v_fma_f32 v2, v45, v2, v45
	v_mul_f32_e32 v2, 0x3f4c422a, v2
	v_mul_f32_e32 v2, -2.0, v2
	v_mul_f32_e32 v2, 0x3fb8aa3b, v2
	v_exp_f32_e32 v37, v2
	s_nop 0
	v_pk_add_f32 v[36:37], v[36:37], 1.0 op_sel_hi:[1,0]
	s_nop 0
	v_div_scale_f32 v2, s[8:9], v37, v37, v45
	v_rcp_f32_e32 v46, v2
	s_nop 0
	v_fma_f32 v47, -v2, v46, 1.0
	v_fmac_f32_e32 v46, v47, v46
	v_div_scale_f32 v47, vcc, v45, v37, v45
	v_mul_f32_e32 v48, v47, v46
	v_fma_f32 v49, -v2, v48, v47
	v_fmac_f32_e32 v48, v49, v46
	v_fma_f32 v2, -v2, v48, v47
	v_div_fmas_f32 v2, v2, v46, v48
	v_div_fixup_f32 v2, v2, v37, v45
	v_div_scale_f32 v37, s[8:9], v36, v36, v44
	v_rcp_f32_e32 v45, v37
	s_nop 0
	v_fma_f32 v46, -v37, v45, 1.0
	v_fmac_f32_e32 v45, v46, v45
	v_div_scale_f32 v46, vcc, v44, v36, v44
	v_mul_f32_e32 v47, v46, v45
	v_fma_f32 v48, -v37, v47, v46
	v_fmac_f32_e32 v47, v48, v45
	v_fma_f32 v37, -v37, v47, v46
	v_div_fmas_f32 v37, v37, v45, v47
	v_div_fixup_f32 v36, v37, v36, v44
	v_cvt_pk_bf16_f32 v36, v36, v2
	v_mul_f32_e32 v2, 0x3d372713, v42
	v_mul_f32_e32 v2, v42, v2
	v_fma_f32 v2, v42, v2, v42
	v_mul_f32_e32 v2, 0x3f4c422a, v2
	v_mul_f32_e32 v2, -2.0, v2
	v_mul_f32_e32 v2, 0x3fb8aa3b, v2
	v_exp_f32_e32 v44, v2
	v_mul_f32_e32 v2, 0x3d372713, v43
	v_mul_f32_e32 v2, v43, v2
	v_fma_f32 v2, v43, v2, v43
	v_mul_f32_e32 v2, 0x3f4c422a, v2
	v_mul_f32_e32 v2, -2.0, v2
	v_mul_f32_e32 v2, 0x3fb8aa3b, v2
	v_exp_f32_e32 v45, v2
	s_nop 0
	v_pk_add_f32 v[44:45], v[44:45], 1.0 op_sel_hi:[1,0]
	s_nop 0
	v_div_scale_f32 v2, s[8:9], v45, v45, v43
	v_rcp_f32_e32 v37, v2
	s_nop 0
	v_fma_f32 v46, -v2, v37, 1.0
	v_fmac_f32_e32 v37, v46, v37
	v_div_scale_f32 v46, vcc, v43, v45, v43
	v_mul_f32_e32 v47, v46, v37
	v_fma_f32 v48, -v2, v47, v46
	v_fmac_f32_e32 v47, v48, v37
	v_fma_f32 v2, -v2, v47, v46
	v_div_fmas_f32 v2, v2, v37, v47
	v_div_scale_f32 v37, s[8:9], v44, v44, v42
	v_div_fixup_f32 v2, v2, v45, v43
	v_rcp_f32_e32 v43, v37
	s_nop 0
	v_fma_f32 v45, -v37, v43, 1.0
	v_fmac_f32_e32 v43, v45, v43
	v_div_scale_f32 v45, vcc, v42, v44, v42
	v_mul_f32_e32 v46, v45, v43
	v_fma_f32 v47, -v37, v46, v45
	v_fmac_f32_e32 v46, v47, v43
	v_fma_f32 v37, -v37, v46, v45
	v_div_fmas_f32 v37, v37, v43, v46
	v_div_fixup_f32 v37, v37, v44, v42
	v_cvt_pk_bf16_f32 v37, v37, v2
	v_mul_f32_e32 v2, 0x3d372713, v38
	v_mul_f32_e32 v2, v38, v2
	v_fma_f32 v2, v38, v2, v38
	v_mul_f32_e32 v2, 0x3f4c422a, v2
	v_mul_f32_e32 v2, -2.0, v2
	v_mul_f32_e32 v2, 0x3fb8aa3b, v2
	v_exp_f32_e32 v42, v2
	v_mul_f32_e32 v2, 0x3d372713, v39
	v_mul_f32_e32 v2, v39, v2
	v_fma_f32 v2, v39, v2, v39
	v_mul_f32_e32 v2, 0x3f4c422a, v2
	v_mul_f32_e32 v2, -2.0, v2
	v_mul_f32_e32 v2, 0x3fb8aa3b, v2
	v_exp_f32_e32 v43, v2
	s_nop 0
	v_pk_add_f32 v[42:43], v[42:43], 1.0 op_sel_hi:[1,0]
	s_nop 0
	v_div_scale_f32 v2, s[8:9], v43, v43, v39
	v_rcp_f32_e32 v44, v2
	s_nop 0
	v_fma_f32 v45, -v2, v44, 1.0
	v_fmac_f32_e32 v44, v45, v44
	v_div_scale_f32 v45, vcc, v39, v43, v39
	v_mul_f32_e32 v46, v45, v44
	v_fma_f32 v47, -v2, v46, v45
	v_fmac_f32_e32 v46, v47, v44
	v_fma_f32 v2, -v2, v46, v45
	v_div_fmas_f32 v2, v2, v44, v46
	v_div_fixup_f32 v2, v2, v43, v39
	v_div_scale_f32 v39, s[8:9], v42, v42, v38
	v_rcp_f32_e32 v43, v39
	s_nop 0
	v_fma_f32 v44, -v39, v43, 1.0
	v_fmac_f32_e32 v43, v44, v43
	v_div_scale_f32 v44, vcc, v38, v42, v38
	v_mul_f32_e32 v45, v44, v43
	v_fma_f32 v46, -v39, v45, v44
	v_fmac_f32_e32 v45, v46, v43
	v_fma_f32 v39, -v39, v45, v44
	v_div_fmas_f32 v39, v39, v43, v45
	v_div_fixup_f32 v38, v39, v42, v38
	v_cvt_pk_bf16_f32 v38, v38, v2
	v_mul_f32_e32 v2, 0x3d372713, v40
	v_mul_f32_e32 v2, v40, v2
	v_fma_f32 v2, v40, v2, v40
	v_mul_f32_e32 v2, 0x3f4c422a, v2
	v_mul_f32_e32 v2, -2.0, v2
	v_mul_f32_e32 v2, 0x3fb8aa3b, v2
	v_exp_f32_e32 v42, v2
	v_mul_f32_e32 v2, 0x3d372713, v41
	v_mul_f32_e32 v2, v41, v2
	v_fma_f32 v2, v41, v2, v41
	v_mul_f32_e32 v2, 0x3f4c422a, v2
	v_mul_f32_e32 v2, -2.0, v2
	v_mul_f32_e32 v2, 0x3fb8aa3b, v2
	v_exp_f32_e32 v43, v2
	s_nop 0
	v_pk_add_f32 v[42:43], v[42:43], 1.0 op_sel_hi:[1,0]
	s_nop 0
	v_div_scale_f32 v2, s[8:9], v43, v43, v41
	v_rcp_f32_e32 v39, v2
	s_nop 0
	v_fma_f32 v44, -v2, v39, 1.0
	v_fmac_f32_e32 v39, v44, v39
	v_div_scale_f32 v44, vcc, v41, v43, v41
	v_mul_f32_e32 v45, v44, v39
	v_fma_f32 v46, -v2, v45, v44
	v_fmac_f32_e32 v45, v46, v39
	v_fma_f32 v2, -v2, v45, v44
	v_div_fmas_f32 v2, v2, v39, v45
	v_div_scale_f32 v39, s[8:9], v42, v42, v40
	v_div_fixup_f32 v2, v2, v43, v41
	v_rcp_f32_e32 v41, v39
	s_nop 0
	v_fma_f32 v43, -v39, v41, 1.0
	v_fmac_f32_e32 v41, v43, v41
	v_div_scale_f32 v43, vcc, v40, v42, v40
	v_mul_f32_e32 v44, v43, v41
	v_fma_f32 v45, -v39, v44, v43
	v_fmac_f32_e32 v44, v45, v41
	v_fma_f32 v39, -v39, v44, v43
	v_div_fmas_f32 v39, v39, v41, v44
	v_div_fixup_f32 v39, v39, v42, v40
	v_cvt_pk_bf16_f32 v39, v39, v2
	global_store_dwordx4 v[112:113], v[36:39], off offset:256
	s_nop 1
	v_pk_add_f32 v[36:37], v[32:33], v[72:73]
	v_pk_add_f32 v[32:33], v[30:31], v[70:71]
	v_mul_f32_e32 v2, 0x3d372713, v36
	v_mul_f32_e32 v2, v36, v2
	v_fma_f32 v2, v36, v2, v36
	v_mul_f32_e32 v2, 0x3f4c422a, v2
	v_mul_f32_e32 v2, -2.0, v2
	v_mul_f32_e32 v2, 0x3fb8aa3b, v2
	v_pk_add_f32 v[30:31], v[28:29], v[68:69]
	v_exp_f32_e32 v28, v2
	v_mul_f32_e32 v2, 0x3d372713, v37
	v_mul_f32_e32 v2, v37, v2
	v_fma_f32 v2, v37, v2, v37
	v_mul_f32_e32 v2, 0x3f4c422a, v2
	v_mul_f32_e32 v2, -2.0, v2
	v_mul_f32_e32 v2, 0x3fb8aa3b, v2
	v_exp_f32_e32 v29, v2
	s_nop 0
	v_pk_add_f32 v[28:29], v[28:29], 1.0 op_sel_hi:[1,0]
	s_nop 0
	v_div_scale_f32 v2, s[8:9], v29, v29, v37
	v_rcp_f32_e32 v38, v2
	s_nop 0
	v_fma_f32 v39, -v2, v38, 1.0
	v_fmac_f32_e32 v38, v39, v38
	v_div_scale_f32 v39, vcc, v37, v29, v37
	v_mul_f32_e32 v40, v39, v38
	v_fma_f32 v41, -v2, v40, v39
	v_fmac_f32_e32 v40, v41, v38
	v_fma_f32 v2, -v2, v40, v39
	v_div_fmas_f32 v2, v2, v38, v40
	v_div_fixup_f32 v2, v2, v29, v37
	v_div_scale_f32 v29, s[8:9], v28, v28, v36
	v_rcp_f32_e32 v37, v29
	v_mov_b32_e32 v41, v3
	v_fma_f32 v38, -v29, v37, 1.0
	v_fmac_f32_e32 v37, v38, v37
	v_div_scale_f32 v38, vcc, v36, v28, v36
	v_mul_f32_e32 v39, v38, v37
	v_fma_f32 v40, -v29, v39, v38
	v_fmac_f32_e32 v39, v40, v37
	v_fma_f32 v29, -v29, v39, v38
	v_div_fmas_f32 v29, v29, v37, v39
	v_div_fixup_f32 v28, v29, v28, v36
	v_cvt_pk_bf16_f32 v28, v28, v2
	v_mul_f32_e32 v2, 0x3d372713, v34
	v_mul_f32_e32 v2, v34, v2
	v_fma_f32 v2, v34, v2, v34
	v_mul_f32_e32 v2, 0x3f4c422a, v2
	v_mul_f32_e32 v2, -2.0, v2
	v_mul_f32_e32 v2, 0x3fb8aa3b, v2
	v_exp_f32_e32 v36, v2
	v_mul_f32_e32 v2, 0x3d372713, v35
	v_mul_f32_e32 v2, v35, v2
	v_fma_f32 v2, v35, v2, v35
	v_mul_f32_e32 v2, 0x3f4c422a, v2
	v_mul_f32_e32 v2, -2.0, v2
	v_mul_f32_e32 v2, 0x3fb8aa3b, v2
	v_exp_f32_e32 v37, v2
	s_nop 0
	v_pk_add_f32 v[36:37], v[36:37], 1.0 op_sel_hi:[1,0]
	s_nop 0
	v_div_scale_f32 v2, s[8:9], v37, v37, v35
	v_rcp_f32_e32 v29, v2
	s_nop 0
	v_fma_f32 v38, -v2, v29, 1.0
	v_fmac_f32_e32 v29, v38, v29
	v_div_scale_f32 v38, vcc, v35, v37, v35
	v_mul_f32_e32 v39, v38, v29
	v_fma_f32 v40, -v2, v39, v38
	v_fmac_f32_e32 v39, v40, v29
	v_fma_f32 v2, -v2, v39, v38
	v_div_fmas_f32 v2, v2, v29, v39
	v_div_scale_f32 v29, s[8:9], v36, v36, v34
	v_div_fixup_f32 v2, v2, v37, v35
	v_rcp_f32_e32 v35, v29
	s_nop 0
	v_fma_f32 v37, -v29, v35, 1.0
	v_fmac_f32_e32 v35, v37, v35
	v_div_scale_f32 v37, vcc, v34, v36, v34
	v_mul_f32_e32 v38, v37, v35
	v_fma_f32 v39, -v29, v38, v37
	v_fmac_f32_e32 v38, v39, v35
	v_fma_f32 v29, -v29, v38, v37
	v_div_fmas_f32 v29, v29, v35, v38
	v_div_fixup_f32 v29, v29, v36, v34
	v_cvt_pk_bf16_f32 v29, v29, v2
	v_mul_f32_e32 v2, 0x3d372713, v30
	v_mul_f32_e32 v2, v30, v2
	v_fma_f32 v2, v30, v2, v30
	v_mul_f32_e32 v2, 0x3f4c422a, v2
	v_mul_f32_e32 v2, -2.0, v2
	v_mul_f32_e32 v2, 0x3fb8aa3b, v2
	v_exp_f32_e32 v34, v2
	v_mul_f32_e32 v2, 0x3d372713, v31
	v_mul_f32_e32 v2, v31, v2
	v_fma_f32 v2, v31, v2, v31
	v_mul_f32_e32 v2, 0x3f4c422a, v2
	v_mul_f32_e32 v2, -2.0, v2
	v_mul_f32_e32 v2, 0x3fb8aa3b, v2
	v_exp_f32_e32 v35, v2
	s_nop 0
	v_pk_add_f32 v[34:35], v[34:35], 1.0 op_sel_hi:[1,0]
	s_nop 0
	v_div_scale_f32 v2, s[8:9], v35, v35, v31
	v_rcp_f32_e32 v36, v2
	s_nop 0
	v_fma_f32 v37, -v2, v36, 1.0
	v_fmac_f32_e32 v36, v37, v36
	v_div_scale_f32 v37, vcc, v31, v35, v31
	v_mul_f32_e32 v38, v37, v36
	v_fma_f32 v39, -v2, v38, v37
	v_fmac_f32_e32 v38, v39, v36
	v_fma_f32 v2, -v2, v38, v37
	v_div_fmas_f32 v2, v2, v36, v38
	v_div_fixup_f32 v2, v2, v35, v31
	v_div_scale_f32 v31, s[8:9], v34, v34, v30
	v_rcp_f32_e32 v35, v31
	s_nop 0
	v_fma_f32 v36, -v31, v35, 1.0
	v_fmac_f32_e32 v35, v36, v35
	v_div_scale_f32 v36, vcc, v30, v34, v30
	v_mul_f32_e32 v37, v36, v35
	v_fma_f32 v38, -v31, v37, v36
	v_fmac_f32_e32 v37, v38, v35
	v_fma_f32 v31, -v31, v37, v36
	v_div_fmas_f32 v31, v31, v35, v37
	v_div_fixup_f32 v30, v31, v34, v30
	v_cvt_pk_bf16_f32 v30, v30, v2
	v_mul_f32_e32 v2, 0x3d372713, v32
	v_mul_f32_e32 v2, v32, v2
	v_fma_f32 v2, v32, v2, v32
	v_mul_f32_e32 v2, 0x3f4c422a, v2
	v_mul_f32_e32 v2, -2.0, v2
	v_mul_f32_e32 v2, 0x3fb8aa3b, v2
	v_exp_f32_e32 v34, v2
	v_mul_f32_e32 v2, 0x3d372713, v33
	v_mul_f32_e32 v2, v33, v2
	v_fma_f32 v2, v33, v2, v33
	v_mul_f32_e32 v2, 0x3f4c422a, v2
	v_mul_f32_e32 v2, -2.0, v2
	v_mul_f32_e32 v2, 0x3fb8aa3b, v2
	v_exp_f32_e32 v35, v2
	s_nop 0
	v_pk_add_f32 v[34:35], v[34:35], 1.0 op_sel_hi:[1,0]
	s_nop 0
	v_div_scale_f32 v2, s[8:9], v35, v35, v33
	v_rcp_f32_e32 v31, v2
	s_nop 0
	v_fma_f32 v36, -v2, v31, 1.0
	v_fmac_f32_e32 v31, v36, v31
	v_div_scale_f32 v36, vcc, v33, v35, v33
	v_mul_f32_e32 v37, v36, v31
	v_fma_f32 v38, -v2, v37, v36
	v_fmac_f32_e32 v37, v38, v31
	v_fma_f32 v2, -v2, v37, v36
	v_div_fmas_f32 v2, v2, v31, v37
	v_div_scale_f32 v31, s[8:9], v34, v34, v32
	v_div_fixup_f32 v2, v2, v35, v33
	v_rcp_f32_e32 v33, v31
	s_nop 0
	v_fma_f32 v35, -v31, v33, 1.0
	v_fmac_f32_e32 v33, v35, v33
	v_div_scale_f32 v35, vcc, v32, v34, v32
	v_mul_f32_e32 v36, v35, v33
	v_fma_f32 v37, -v31, v36, v35
	v_fmac_f32_e32 v36, v37, v33
	v_fma_f32 v31, -v31, v36, v35
	v_div_fmas_f32 v31, v31, v33, v36
	v_div_fixup_f32 v31, v31, v34, v32
	v_cvt_pk_bf16_f32 v31, v31, v2
	global_store_dwordx4 v[104:105], v[28:31], off offset:256
	s_nop 1
	v_pk_add_f32 v[28:29], v[24:25], v[72:73]
	v_pk_add_f32 v[24:25], v[22:23], v[70:71]
	v_mul_f32_e32 v2, 0x3d372713, v28
	v_mul_f32_e32 v2, v28, v2
	v_fma_f32 v2, v28, v2, v28
	v_mul_f32_e32 v2, 0x3f4c422a, v2
	v_mul_f32_e32 v2, -2.0, v2
	v_mul_f32_e32 v2, 0x3fb8aa3b, v2
	v_pk_add_f32 v[22:23], v[20:21], v[68:69]
	v_exp_f32_e32 v20, v2
	v_mul_f32_e32 v2, 0x3d372713, v29
	v_mul_f32_e32 v2, v29, v2
	v_fma_f32 v2, v29, v2, v29
	v_mul_f32_e32 v2, 0x3f4c422a, v2
	v_mul_f32_e32 v2, -2.0, v2
	v_mul_f32_e32 v2, 0x3fb8aa3b, v2
	v_exp_f32_e32 v21, v2
	s_nop 0
	v_pk_add_f32 v[20:21], v[20:21], 1.0 op_sel_hi:[1,0]
	s_nop 0
	v_div_scale_f32 v2, s[8:9], v21, v21, v29
	v_rcp_f32_e32 v30, v2
	s_nop 0
	v_fma_f32 v31, -v2, v30, 1.0
	v_fmac_f32_e32 v30, v31, v30
	v_div_scale_f32 v31, vcc, v29, v21, v29
	v_mul_f32_e32 v32, v31, v30
	v_fma_f32 v33, -v2, v32, v31
	v_fmac_f32_e32 v32, v33, v30
	v_fma_f32 v2, -v2, v32, v31
	v_div_fmas_f32 v2, v2, v30, v32
	v_div_fixup_f32 v2, v2, v21, v29
	v_div_scale_f32 v21, s[8:9], v20, v20, v28
	v_rcp_f32_e32 v29, v21
	s_nop 0
	v_fma_f32 v30, -v21, v29, 1.0
	v_fmac_f32_e32 v29, v30, v29
	v_div_scale_f32 v30, vcc, v28, v20, v28
	v_mul_f32_e32 v31, v30, v29
	v_fma_f32 v32, -v21, v31, v30
	v_fmac_f32_e32 v31, v32, v29
	v_fma_f32 v21, -v21, v31, v30
	v_div_fmas_f32 v21, v21, v29, v31
	v_div_fixup_f32 v20, v21, v20, v28
	v_cvt_pk_bf16_f32 v20, v20, v2
	v_mul_f32_e32 v2, 0x3d372713, v26
	v_mul_f32_e32 v2, v26, v2
	v_fma_f32 v2, v26, v2, v26
	v_mul_f32_e32 v2, 0x3f4c422a, v2
	v_mul_f32_e32 v2, -2.0, v2
	v_mul_f32_e32 v2, 0x3fb8aa3b, v2
	v_exp_f32_e32 v28, v2
	v_mul_f32_e32 v2, 0x3d372713, v27
	v_mul_f32_e32 v2, v27, v2
	v_fma_f32 v2, v27, v2, v27
	v_mul_f32_e32 v2, 0x3f4c422a, v2
	v_mul_f32_e32 v2, -2.0, v2
	v_mul_f32_e32 v2, 0x3fb8aa3b, v2
	v_exp_f32_e32 v29, v2
	s_nop 0
	v_pk_add_f32 v[28:29], v[28:29], 1.0 op_sel_hi:[1,0]
	s_nop 0
	v_div_scale_f32 v2, s[8:9], v29, v29, v27
	v_rcp_f32_e32 v21, v2
	s_nop 0
	v_fma_f32 v30, -v2, v21, 1.0
	v_fmac_f32_e32 v21, v30, v21
	v_div_scale_f32 v30, vcc, v27, v29, v27
	v_mul_f32_e32 v31, v30, v21
	v_fma_f32 v32, -v2, v31, v30
	v_fmac_f32_e32 v31, v32, v21
	v_fma_f32 v2, -v2, v31, v30
	v_div_fmas_f32 v2, v2, v21, v31
	v_div_scale_f32 v21, s[8:9], v28, v28, v26
	v_div_fixup_f32 v2, v2, v29, v27
	v_rcp_f32_e32 v27, v21
	s_nop 0
	v_fma_f32 v29, -v21, v27, 1.0
	v_fmac_f32_e32 v27, v29, v27
	v_div_scale_f32 v29, vcc, v26, v28, v26
	v_mul_f32_e32 v30, v29, v27
	v_fma_f32 v31, -v21, v30, v29
	v_fmac_f32_e32 v30, v31, v27
	v_fma_f32 v21, -v21, v30, v29
	v_div_fmas_f32 v21, v21, v27, v30
	v_div_fixup_f32 v21, v21, v28, v26
	v_cvt_pk_bf16_f32 v21, v21, v2
	v_mul_f32_e32 v2, 0x3d372713, v22
	v_mul_f32_e32 v2, v22, v2
	v_fma_f32 v2, v22, v2, v22
	v_mul_f32_e32 v2, 0x3f4c422a, v2
	v_mul_f32_e32 v2, -2.0, v2
	v_mul_f32_e32 v2, 0x3fb8aa3b, v2
	v_exp_f32_e32 v26, v2
	v_mul_f32_e32 v2, 0x3d372713, v23
	v_mul_f32_e32 v2, v23, v2
	v_fma_f32 v2, v23, v2, v23
	v_mul_f32_e32 v2, 0x3f4c422a, v2
	v_mul_f32_e32 v2, -2.0, v2
	v_mul_f32_e32 v2, 0x3fb8aa3b, v2
	v_exp_f32_e32 v27, v2
	s_nop 0
	v_pk_add_f32 v[26:27], v[26:27], 1.0 op_sel_hi:[1,0]
	s_nop 0
	v_div_scale_f32 v2, s[8:9], v27, v27, v23
	v_rcp_f32_e32 v28, v2
	s_nop 0
	v_fma_f32 v29, -v2, v28, 1.0
	v_fmac_f32_e32 v28, v29, v28
	v_div_scale_f32 v29, vcc, v23, v27, v23
	v_mul_f32_e32 v30, v29, v28
	v_fma_f32 v31, -v2, v30, v29
	v_fmac_f32_e32 v30, v31, v28
	v_fma_f32 v2, -v2, v30, v29
	v_div_fmas_f32 v2, v2, v28, v30
	v_div_fixup_f32 v2, v2, v27, v23
	v_div_scale_f32 v23, s[8:9], v26, v26, v22
	v_rcp_f32_e32 v27, v23
	s_nop 0
	v_fma_f32 v28, -v23, v27, 1.0
	v_fmac_f32_e32 v27, v28, v27
	v_div_scale_f32 v28, vcc, v22, v26, v22
	v_mul_f32_e32 v29, v28, v27
	v_fma_f32 v30, -v23, v29, v28
	v_fmac_f32_e32 v29, v30, v27
	v_fma_f32 v23, -v23, v29, v28
	v_div_fmas_f32 v23, v23, v27, v29
	v_div_fixup_f32 v22, v23, v26, v22
	v_cvt_pk_bf16_f32 v22, v22, v2
	v_mul_f32_e32 v2, 0x3d372713, v24
	v_mul_f32_e32 v2, v24, v2
	v_fma_f32 v2, v24, v2, v24
	v_mul_f32_e32 v2, 0x3f4c422a, v2
	v_mul_f32_e32 v2, -2.0, v2
	v_mul_f32_e32 v2, 0x3fb8aa3b, v2
	v_exp_f32_e32 v26, v2
	v_mul_f32_e32 v2, 0x3d372713, v25
	v_mul_f32_e32 v2, v25, v2
	v_fma_f32 v2, v25, v2, v25
	v_mul_f32_e32 v2, 0x3f4c422a, v2
	v_mul_f32_e32 v2, -2.0, v2
	v_mul_f32_e32 v2, 0x3fb8aa3b, v2
	v_exp_f32_e32 v27, v2
	s_nop 0
	v_pk_add_f32 v[26:27], v[26:27], 1.0 op_sel_hi:[1,0]
	s_nop 0
	v_div_scale_f32 v2, s[8:9], v27, v27, v25
	v_rcp_f32_e32 v23, v2
	s_nop 0
	v_fma_f32 v28, -v2, v23, 1.0
	v_fmac_f32_e32 v23, v28, v23
	v_div_scale_f32 v28, vcc, v25, v27, v25
	v_mul_f32_e32 v29, v28, v23
	v_fma_f32 v30, -v2, v29, v28
	v_fmac_f32_e32 v29, v30, v23
	v_fma_f32 v2, -v2, v29, v28
	v_div_fmas_f32 v2, v2, v23, v29
	v_div_scale_f32 v23, s[8:9], v26, v26, v24
	v_div_fixup_f32 v2, v2, v27, v25
	v_rcp_f32_e32 v25, v23
	s_nop 0
	v_fma_f32 v27, -v23, v25, 1.0
	v_fmac_f32_e32 v25, v27, v25
	v_div_scale_f32 v27, vcc, v24, v26, v24
	v_mul_f32_e32 v28, v27, v25
	v_fma_f32 v29, -v23, v28, v27
	v_fmac_f32_e32 v28, v29, v25
	v_fma_f32 v23, -v23, v28, v27
	v_div_fmas_f32 v23, v23, v25, v28
	v_div_fixup_f32 v23, v23, v26, v24
	v_cvt_pk_bf16_f32 v23, v23, v2
	global_store_dwordx4 v[96:97], v[20:23], off offset:256
	v_mov_b32_e32 v29, v3
	s_nop 0
	v_pk_add_f32 v[20:21], v[16:17], v[72:73]
	v_pk_add_f32 v[16:17], v[14:15], v[70:71]
	v_mul_f32_e32 v2, 0x3d372713, v20
	v_mul_f32_e32 v2, v20, v2
	v_fma_f32 v2, v20, v2, v20
	v_mul_f32_e32 v2, 0x3f4c422a, v2
	v_mul_f32_e32 v2, -2.0, v2
	v_mul_f32_e32 v2, 0x3fb8aa3b, v2
	v_pk_add_f32 v[14:15], v[12:13], v[68:69]
	v_exp_f32_e32 v12, v2
	v_mul_f32_e32 v2, 0x3d372713, v21
	v_mul_f32_e32 v2, v21, v2
	v_fma_f32 v2, v21, v2, v21
	v_mul_f32_e32 v2, 0x3f4c422a, v2
	v_mul_f32_e32 v2, -2.0, v2
	v_mul_f32_e32 v2, 0x3fb8aa3b, v2
	v_exp_f32_e32 v13, v2
	s_nop 0
	v_pk_add_f32 v[12:13], v[12:13], 1.0 op_sel_hi:[1,0]
	s_nop 0
	v_div_scale_f32 v2, s[8:9], v13, v13, v21
	v_rcp_f32_e32 v22, v2
	s_nop 0
	v_fma_f32 v23, -v2, v22, 1.0
	v_fmac_f32_e32 v22, v23, v22
	v_div_scale_f32 v23, vcc, v21, v13, v21
	v_mul_f32_e32 v24, v23, v22
	v_fma_f32 v25, -v2, v24, v23
	v_fmac_f32_e32 v24, v25, v22
	v_fma_f32 v2, -v2, v24, v23
	v_div_fmas_f32 v2, v2, v22, v24
	v_div_fixup_f32 v2, v2, v13, v21
	v_div_scale_f32 v13, s[8:9], v12, v12, v20
	v_rcp_f32_e32 v21, v13
	s_nop 0
	v_fma_f32 v22, -v13, v21, 1.0
	v_fmac_f32_e32 v21, v22, v21
	v_div_scale_f32 v22, vcc, v20, v12, v20
	v_mul_f32_e32 v23, v22, v21
	v_fma_f32 v24, -v13, v23, v22
	v_fmac_f32_e32 v23, v24, v21
	v_fma_f32 v13, -v13, v23, v22
	v_div_fmas_f32 v13, v13, v21, v23
	v_div_fixup_f32 v12, v13, v12, v20
	v_cvt_pk_bf16_f32 v12, v12, v2
	v_mul_f32_e32 v2, 0x3d372713, v18
	v_mul_f32_e32 v2, v18, v2
	v_fma_f32 v2, v18, v2, v18
	v_mul_f32_e32 v2, 0x3f4c422a, v2
	v_mul_f32_e32 v2, -2.0, v2
	v_mul_f32_e32 v2, 0x3fb8aa3b, v2
	v_exp_f32_e32 v20, v2
	v_mul_f32_e32 v2, 0x3d372713, v19
	v_mul_f32_e32 v2, v19, v2
	v_fma_f32 v2, v19, v2, v19
	v_mul_f32_e32 v2, 0x3f4c422a, v2
	v_mul_f32_e32 v2, -2.0, v2
	v_mul_f32_e32 v2, 0x3fb8aa3b, v2
	v_exp_f32_e32 v21, v2
	s_nop 0
	v_pk_add_f32 v[20:21], v[20:21], 1.0 op_sel_hi:[1,0]
	s_nop 0
	v_div_scale_f32 v2, s[8:9], v21, v21, v19
	v_rcp_f32_e32 v13, v2
	s_nop 0
	v_fma_f32 v22, -v2, v13, 1.0
	v_fmac_f32_e32 v13, v22, v13
	v_div_scale_f32 v22, vcc, v19, v21, v19
	v_mul_f32_e32 v23, v22, v13
	v_fma_f32 v24, -v2, v23, v22
	v_fmac_f32_e32 v23, v24, v13
	v_fma_f32 v2, -v2, v23, v22
	v_div_fmas_f32 v2, v2, v13, v23
	v_div_scale_f32 v13, s[8:9], v20, v20, v18
	v_div_fixup_f32 v2, v2, v21, v19
	v_rcp_f32_e32 v19, v13
	s_nop 0
	v_fma_f32 v21, -v13, v19, 1.0
	v_fmac_f32_e32 v19, v21, v19
	v_div_scale_f32 v21, vcc, v18, v20, v18
	v_mul_f32_e32 v22, v21, v19
	v_fma_f32 v23, -v13, v22, v21
	v_fmac_f32_e32 v22, v23, v19
	v_fma_f32 v13, -v13, v22, v21
	v_div_fmas_f32 v13, v13, v19, v22
	v_div_fixup_f32 v13, v13, v20, v18
	v_cvt_pk_bf16_f32 v13, v13, v2
	v_mul_f32_e32 v2, 0x3d372713, v14
	v_mul_f32_e32 v2, v14, v2
	v_fma_f32 v2, v14, v2, v14
	v_mul_f32_e32 v2, 0x3f4c422a, v2
	v_mul_f32_e32 v2, -2.0, v2
	v_mul_f32_e32 v2, 0x3fb8aa3b, v2
	v_exp_f32_e32 v18, v2
	v_mul_f32_e32 v2, 0x3d372713, v15
	v_mul_f32_e32 v2, v15, v2
	v_fma_f32 v2, v15, v2, v15
	v_mul_f32_e32 v2, 0x3f4c422a, v2
	v_mul_f32_e32 v2, -2.0, v2
	v_mul_f32_e32 v2, 0x3fb8aa3b, v2
	v_exp_f32_e32 v19, v2
	s_nop 0
	v_pk_add_f32 v[18:19], v[18:19], 1.0 op_sel_hi:[1,0]
	s_nop 0
	v_div_scale_f32 v2, s[8:9], v19, v19, v15
	v_rcp_f32_e32 v20, v2
	s_nop 0
	v_fma_f32 v21, -v2, v20, 1.0
	v_fmac_f32_e32 v20, v21, v20
	v_div_scale_f32 v21, vcc, v15, v19, v15
	v_mul_f32_e32 v22, v21, v20
	v_fma_f32 v23, -v2, v22, v21
	v_fmac_f32_e32 v22, v23, v20
	v_fma_f32 v2, -v2, v22, v21
	v_div_fmas_f32 v2, v2, v20, v22
	v_div_fixup_f32 v2, v2, v19, v15
	v_div_scale_f32 v15, s[8:9], v18, v18, v14
	v_rcp_f32_e32 v19, v15
	s_nop 0
	v_fma_f32 v20, -v15, v19, 1.0
	v_fmac_f32_e32 v19, v20, v19
	v_div_scale_f32 v20, vcc, v14, v18, v14
	v_mul_f32_e32 v21, v20, v19
	v_fma_f32 v22, -v15, v21, v20
	v_fmac_f32_e32 v21, v22, v19
	v_fma_f32 v15, -v15, v21, v20
	v_div_fmas_f32 v15, v15, v19, v21
	v_div_fixup_f32 v14, v15, v18, v14
	v_cvt_pk_bf16_f32 v14, v14, v2
	v_mul_f32_e32 v2, 0x3d372713, v16
	v_mul_f32_e32 v2, v16, v2
	v_fma_f32 v2, v16, v2, v16
	v_mul_f32_e32 v2, 0x3f4c422a, v2
	v_mul_f32_e32 v2, -2.0, v2
	v_mul_f32_e32 v2, 0x3fb8aa3b, v2
	v_exp_f32_e32 v18, v2
	v_mul_f32_e32 v2, 0x3d372713, v17
	v_mul_f32_e32 v2, v17, v2
	v_fma_f32 v2, v17, v2, v17
	v_mul_f32_e32 v2, 0x3f4c422a, v2
	v_mul_f32_e32 v2, -2.0, v2
	v_mul_f32_e32 v2, 0x3fb8aa3b, v2
	v_exp_f32_e32 v19, v2
	s_nop 0
	v_pk_add_f32 v[18:19], v[18:19], 1.0 op_sel_hi:[1,0]
	s_nop 0
	v_div_scale_f32 v2, s[8:9], v19, v19, v17
	v_rcp_f32_e32 v15, v2
	s_nop 0
	v_fma_f32 v20, -v2, v15, 1.0
	v_fmac_f32_e32 v15, v20, v15
	v_div_scale_f32 v20, vcc, v17, v19, v17
	v_mul_f32_e32 v21, v20, v15
	v_fma_f32 v22, -v2, v21, v20
	v_fmac_f32_e32 v21, v22, v15
	v_fma_f32 v2, -v2, v21, v20
	v_div_fmas_f32 v2, v2, v15, v21
	v_div_scale_f32 v15, s[8:9], v18, v18, v16
	v_div_fixup_f32 v2, v2, v19, v17
	v_rcp_f32_e32 v17, v15
	s_nop 0
	v_fma_f32 v19, -v15, v17, 1.0
	v_fmac_f32_e32 v17, v19, v17
	v_div_scale_f32 v19, vcc, v16, v18, v16
	v_mul_f32_e32 v20, v19, v17
	v_fma_f32 v21, -v15, v20, v19
	v_fmac_f32_e32 v20, v21, v17
	v_fma_f32 v15, -v15, v20, v19
	v_div_fmas_f32 v15, v15, v17, v20
	v_div_fixup_f32 v15, v15, v18, v16
	v_cvt_pk_bf16_f32 v15, v15, v2
	global_store_dwordx4 v[80:81], v[12:15], off offset:256
	s_nop 1
	v_pk_add_f32 v[12:13], v[8:9], v[72:73]
	v_pk_add_f32 v[8:9], v[6:7], v[70:71]
	v_mul_f32_e32 v2, 0x3d372713, v12
	v_mul_f32_e32 v2, v12, v2
	v_fma_f32 v2, v12, v2, v12
	v_mul_f32_e32 v2, 0x3f4c422a, v2
	v_mul_f32_e32 v2, -2.0, v2
	v_mul_f32_e32 v2, 0x3fb8aa3b, v2
	v_pk_add_f32 v[6:7], v[4:5], v[68:69]
	v_exp_f32_e32 v4, v2
	v_mul_f32_e32 v2, 0x3d372713, v13
	v_mul_f32_e32 v2, v13, v2
	v_fma_f32 v2, v13, v2, v13
	v_mul_f32_e32 v2, 0x3f4c422a, v2
	v_mul_f32_e32 v2, -2.0, v2
	v_mul_f32_e32 v2, 0x3fb8aa3b, v2
	v_exp_f32_e32 v5, v2
	v_mov_b32_e32 v73, v3
	v_mov_b32_e32 v71, v3
	v_pk_add_f32 v[4:5], v[4:5], 1.0 op_sel_hi:[1,0]
	s_nop 0
	v_div_scale_f32 v2, s[8:9], v5, v5, v13
	v_rcp_f32_e32 v14, v2
	s_nop 0
	v_fma_f32 v15, -v2, v14, 1.0
	v_fmac_f32_e32 v14, v15, v14
	v_div_scale_f32 v15, vcc, v13, v5, v13
	v_mul_f32_e32 v16, v15, v14
	v_fma_f32 v17, -v2, v16, v15
	v_fmac_f32_e32 v16, v17, v14
	v_fma_f32 v2, -v2, v16, v15
	v_div_fmas_f32 v2, v2, v14, v16
	v_div_fixup_f32 v2, v2, v5, v13
	v_div_scale_f32 v5, s[8:9], v4, v4, v12
	v_rcp_f32_e32 v13, v5
	s_nop 0
	v_fma_f32 v14, -v5, v13, 1.0
	v_fmac_f32_e32 v13, v14, v13
	v_div_scale_f32 v14, vcc, v12, v4, v12
	v_mul_f32_e32 v15, v14, v13
	v_fma_f32 v16, -v5, v15, v14
	v_fmac_f32_e32 v15, v16, v13
	v_fma_f32 v5, -v5, v15, v14
	v_div_fmas_f32 v5, v5, v13, v15
	v_div_fixup_f32 v4, v5, v4, v12
	v_cvt_pk_bf16_f32 v4, v4, v2
	v_mul_f32_e32 v2, 0x3d372713, v10
	v_mul_f32_e32 v2, v10, v2
	v_fma_f32 v2, v10, v2, v10
	v_mul_f32_e32 v2, 0x3f4c422a, v2
	v_mul_f32_e32 v2, -2.0, v2
	v_mul_f32_e32 v2, 0x3fb8aa3b, v2
	v_exp_f32_e32 v12, v2
	v_mul_f32_e32 v2, 0x3d372713, v11
	v_mul_f32_e32 v2, v11, v2
	v_fma_f32 v2, v11, v2, v11
	v_mul_f32_e32 v2, 0x3f4c422a, v2
	v_mul_f32_e32 v2, -2.0, v2
	v_mul_f32_e32 v2, 0x3fb8aa3b, v2
	v_exp_f32_e32 v13, v2
	s_nop 0
	v_pk_add_f32 v[12:13], v[12:13], 1.0 op_sel_hi:[1,0]
	s_nop 0
	v_div_scale_f32 v2, s[8:9], v13, v13, v11
	v_rcp_f32_e32 v5, v2
	s_nop 0
	v_fma_f32 v14, -v2, v5, 1.0
	v_fmac_f32_e32 v5, v14, v5
	v_div_scale_f32 v14, vcc, v11, v13, v11
	v_mul_f32_e32 v15, v14, v5
	v_fma_f32 v16, -v2, v15, v14
	v_fmac_f32_e32 v15, v16, v5
	v_fma_f32 v2, -v2, v15, v14
	v_div_fmas_f32 v2, v2, v5, v15
	v_div_scale_f32 v5, s[8:9], v12, v12, v10
	v_div_fixup_f32 v2, v2, v13, v11
	v_rcp_f32_e32 v11, v5
	s_nop 0
	v_fma_f32 v13, -v5, v11, 1.0
	v_fmac_f32_e32 v11, v13, v11
	v_div_scale_f32 v13, vcc, v10, v12, v10
	v_mul_f32_e32 v14, v13, v11
	v_fma_f32 v15, -v5, v14, v13
	v_fmac_f32_e32 v14, v15, v11
	v_fma_f32 v5, -v5, v14, v13
	v_div_fmas_f32 v5, v5, v11, v14
	v_div_fixup_f32 v5, v5, v12, v10
	v_cvt_pk_bf16_f32 v5, v5, v2
	v_mul_f32_e32 v2, 0x3d372713, v6
	v_mul_f32_e32 v2, v6, v2
	v_fma_f32 v2, v6, v2, v6
	v_mul_f32_e32 v2, 0x3f4c422a, v2
	v_mul_f32_e32 v2, -2.0, v2
	v_mul_f32_e32 v2, 0x3fb8aa3b, v2
	v_exp_f32_e32 v10, v2
	v_mul_f32_e32 v2, 0x3d372713, v7
	v_mul_f32_e32 v2, v7, v2
	v_fma_f32 v2, v7, v2, v7
	v_mul_f32_e32 v2, 0x3f4c422a, v2
	v_mul_f32_e32 v2, -2.0, v2
	v_mul_f32_e32 v2, 0x3fb8aa3b, v2
	v_exp_f32_e32 v11, v2
	s_nop 0
	v_pk_add_f32 v[10:11], v[10:11], 1.0 op_sel_hi:[1,0]
	s_nop 0
	v_div_scale_f32 v2, s[8:9], v11, v11, v7
	v_rcp_f32_e32 v12, v2
	s_nop 0
	v_fma_f32 v13, -v2, v12, 1.0
	v_fmac_f32_e32 v12, v13, v12
	v_div_scale_f32 v13, vcc, v7, v11, v7
	v_mul_f32_e32 v14, v13, v12
	v_fma_f32 v15, -v2, v14, v13
	v_fmac_f32_e32 v14, v15, v12
	v_fma_f32 v2, -v2, v14, v13
	v_div_fmas_f32 v2, v2, v12, v14
	v_div_fixup_f32 v2, v2, v11, v7
	v_div_scale_f32 v7, s[8:9], v10, v10, v6
	v_rcp_f32_e32 v11, v7
	s_nop 0
	v_fma_f32 v12, -v7, v11, 1.0
	v_fmac_f32_e32 v11, v12, v11
	v_div_scale_f32 v12, vcc, v6, v10, v6
	v_mul_f32_e32 v13, v12, v11
	v_fma_f32 v14, -v7, v13, v12
	v_fmac_f32_e32 v13, v14, v11
	v_fma_f32 v7, -v7, v13, v12
	v_div_fmas_f32 v7, v7, v11, v13
	v_div_fixup_f32 v6, v7, v10, v6
	v_cvt_pk_bf16_f32 v6, v6, v2
	v_mul_f32_e32 v2, 0x3d372713, v8
	v_mul_f32_e32 v2, v8, v2
	v_fma_f32 v2, v8, v2, v8
	v_mul_f32_e32 v2, 0x3f4c422a, v2
	v_mul_f32_e32 v2, -2.0, v2
	v_mul_f32_e32 v2, 0x3fb8aa3b, v2
	v_exp_f32_e32 v10, v2
	v_mul_f32_e32 v2, 0x3d372713, v9
	v_mul_f32_e32 v2, v9, v2
	v_fma_f32 v2, v9, v2, v9
	v_mul_f32_e32 v2, 0x3f4c422a, v2
	v_mul_f32_e32 v2, -2.0, v2
	v_mul_f32_e32 v2, 0x3fb8aa3b, v2
	v_exp_f32_e32 v11, v2
	s_nop 0
	v_pk_add_f32 v[10:11], v[10:11], 1.0 op_sel_hi:[1,0]
	s_nop 0
	v_div_scale_f32 v2, s[8:9], v11, v11, v9
	v_rcp_f32_e32 v7, v2
	s_nop 0
	v_fma_f32 v12, -v2, v7, 1.0
	v_fmac_f32_e32 v7, v12, v7
	v_div_scale_f32 v12, vcc, v9, v11, v9
	v_mul_f32_e32 v13, v12, v7
	v_fma_f32 v14, -v2, v13, v12
	v_fmac_f32_e32 v13, v14, v7
	v_fma_f32 v2, -v2, v13, v12
	v_div_fmas_f32 v2, v2, v7, v13
	v_div_scale_f32 v7, s[8:9], v10, v10, v8
	v_div_fixup_f32 v2, v2, v11, v9
	v_rcp_f32_e32 v9, v7
	s_lshl_b64 s[8:9], s[2:3], 15
	s_add_u32 s8, s4, s8
	s_addc_u32 s9, s5, s9
	v_fma_f32 v11, -v7, v9, 1.0
	v_fmac_f32_e32 v9, v11, v9
	v_div_scale_f32 v11, vcc, v8, v10, v8
	v_mul_f32_e32 v12, v11, v9
	v_fma_f32 v13, -v7, v12, v11
	v_fmac_f32_e32 v12, v13, v9
	v_fma_f32 v7, -v7, v12, v11
	v_div_fmas_f32 v7, v7, v9, v12
	v_div_fixup_f32 v7, v7, v10, v8
	v_cvt_pk_bf16_f32 v7, v7, v2
	global_store_dwordx4 v[76:77], v[4:7], off offset:256
	v_mov_b32_e32 v2, v0
	s_waitcnt vmcnt(0)
	s_barrier
	s_mul_hi_i32 s3, s2, 0x2200000
	v_readfirstlane_b32 s1, v2
	s_add_u32 s24, s20, s24
	s_mul_i32 s2, s2, 0xfffef0
	s_addc_u32 s25, s21, s3
	s_add_i32 s2, s2, s0
	s_ashr_i32 s1, s1, 1
	s_lshl_b32 s0, s2, 8
	s_andn2_b32 s1, s1, 31
	s_add_i32 s1, s1, s0
	v_and_b32_e32 v24, 15, v2
	v_or_b32_e32 v26, s1, v24
	v_bfe_u32 v76, v2, 4, 2
	v_ashrrev_i32_e32 v27, 31, v26
	v_lshlrev_b64 v[4:5], 9, v[26:27]
	v_lshlrev_b32_e32 v28, 4, v76
	v_lshl_add_u64 v[4:5], s[24:25], 0, v[4:5]
	v_lshl_add_u64 v[74:75], s[8:9], 0, v[28:29]
	v_lshlrev_b32_e32 v40, 9, v24
	v_lshl_add_u64 v[4:5], v[4:5], 0, v[28:29]
	v_lshl_add_u64 v[24:25], v[74:75], 0, v[40:41]
	global_load_dwordx4 v[36:39], v[4:5], off
	global_load_dwordx4 v[42:45], v[4:5], off offset:64
	global_load_dwordx4 v[48:51], v[4:5], off offset:128
	global_load_dwordx4 v[20:23], v[4:5], off offset:192
	global_load_dwordx4 v[16:19], v[4:5], off offset:256
	global_load_dwordx4 v[12:15], v[4:5], off offset:320
	global_load_dwordx4 v[8:11], v[4:5], off offset:384
	s_nop 0
	global_load_dwordx4 v[4:7], v[4:5], off offset:448
	v_or_b32_e32 v72, 0x2000, v40
	global_load_dwordx4 v[102:105], v[24:25], off
	v_lshl_add_u64 v[30:31], v[74:75], 0, v[72:73]
	global_load_dwordx4 v[106:109], v[30:31], off
	v_or_b32_e32 v70, 0x4000, v40
	v_lshl_add_u64 v[32:33], v[74:75], 0, v[70:71]
	global_load_dwordx4 v[110:113], v[32:33], off
	v_lshl_add_u64 v[46:47], v[74:75], 0, 64
	v_or_b32_e32 v62, 0x6000, v40
	v_mov_b32_e32 v63, v3
	v_lshl_add_u64 v[34:35], v[74:75], 0, v[62:63]
	global_load_dwordx4 v[114:117], v[34:35], off
	s_waitcnt vmcnt(3)
	v_mfma_f32_16x16x32_bf16 v[52:55], v[102:105], v[36:39], 0
	global_load_dwordx4 v[118:121], v[24:25], off offset:64
	v_lshl_add_u64 v[40:41], v[46:47], 0, v[72:73]
	v_lshl_add_u64 v[60:61], v[74:75], 0, s[18:19]
	s_waitcnt vmcnt(3)
	v_mfma_f32_16x16x32_bf16 v[56:59], v[106:109], v[36:39], 0
	global_load_dwordx4 v[122:125], v[40:41], off
	s_mov_b64 s[0:1], 0xc0
	v_lshl_add_u64 v[68:69], v[74:75], 0, s[0:1]
	s_waitcnt vmcnt(3)
	v_mfma_f32_16x16x32_bf16 v[64:67], v[110:113], v[36:39], 0
	s_nop 0
	s_waitcnt vmcnt(2)
	v_mfma_f32_16x16x32_bf16 v[78:81], v[114:117], v[36:39], 0
	s_nop 2
	v_lshl_add_u64 v[38:39], v[46:47], 0, v[70:71]
	global_load_dwordx4 v[126:129], v[38:39], off
	v_lshl_add_u64 v[36:37], v[46:47], 0, v[62:63]
	global_load_dwordx4 v[130:133], v[36:37], off
	s_mov_b64 s[0:1], 0x100
	v_lshlrev_b32_e32 v2, 3, v76
	s_waitcnt vmcnt(3)
	v_mfma_f32_16x16x32_bf16 v[52:55], v[118:121], v[42:45], v[52:55]
	global_load_dwordx4 v[134:137], v[24:25], off offset:128
	s_waitcnt vmcnt(3)
	v_mfma_f32_16x16x32_bf16 v[56:59], v[122:125], v[42:45], v[56:59]
	s_waitcnt vmcnt(2)
	v_mfma_f32_16x16x32_bf16 v[64:67], v[126:129], v[42:45], v[64:67]
	s_nop 0
	s_waitcnt vmcnt(1)
	v_mfma_f32_16x16x32_bf16 v[78:81], v[130:133], v[42:45], v[78:81]
	s_nop 2
	v_lshl_add_u64 v[42:43], v[60:61], 0, v[72:73]
	global_load_dwordx4 v[102:105], v[42:43], off
	v_lshl_add_u64 v[44:45], v[60:61], 0, v[70:71]
	global_load_dwordx4 v[106:109], v[44:45], off
	v_lshl_add_u64 v[46:47], v[60:61], 0, v[62:63]
	global_load_dwordx4 v[110:113], v[46:47], off
	s_waitcnt vmcnt(3)
	v_mfma_f32_16x16x32_bf16 v[52:55], v[134:137], v[48:51], v[52:55]
	global_load_dwordx4 v[114:117], v[24:25], off offset:192
	s_waitcnt vmcnt(3)
	v_mfma_f32_16x16x32_bf16 v[56:59], v[102:105], v[48:51], v[56:59]
	s_waitcnt vmcnt(2)
	v_mfma_f32_16x16x32_bf16 v[64:67], v[106:109], v[48:51], v[64:67]
	s_waitcnt vmcnt(1)
	v_mfma_f32_16x16x32_bf16 v[78:81], v[110:113], v[48:51], v[78:81]
	s_waitcnt vmcnt(0)
	v_mfma_f32_16x16x32_bf16 v[82:85], v[114:117], v[20:23], v[52:55]
	s_nop 2
	v_lshl_add_u64 v[52:53], v[68:69], 0, v[72:73]
	global_load_dwordx4 v[118:121], v[52:53], off
	v_lshl_add_u64 v[50:51], v[68:69], 0, v[70:71]
	s_nop 1
	global_load_dwordx4 v[122:125], v[50:51], off
	v_lshl_add_u64 v[48:49], v[68:69], 0, v[62:63]
	global_load_dwordx4 v[126:129], v[48:49], off
	v_lshl_add_u64 v[68:69], v[74:75], 0, s[0:1]
	s_mov_b64 s[0:1], 0x140
	global_load_dwordx4 v[130:133], v[24:25], off offset:256
	s_waitcnt vmcnt(3)
	v_mfma_f32_16x16x32_bf16 v[54:57], v[118:121], v[20:23], v[56:59]
	s_waitcnt vmcnt(2)
	v_mfma_f32_16x16x32_bf16 v[58:61], v[122:125], v[20:23], v[64:67]
	s_nop 2
	s_waitcnt vmcnt(1)
	v_mfma_f32_16x16x32_bf16 v[64:67], v[126:129], v[20:23], v[78:81]
	s_nop 2
	v_lshl_add_u64 v[20:21], v[68:69], 0, v[72:73]
	s_nop 1
	global_load_dwordx4 v[134:137], v[20:21], off
	v_lshl_add_u64 v[22:23], v[68:69], 0, v[70:71]
	global_load_dwordx4 v[102:105], v[22:23], off
	s_waitcnt vmcnt(2)
	v_mfma_f32_16x16x32_bf16 v[78:81], v[130:133], v[16:19], v[82:85]
	s_waitcnt vmcnt(1)
	v_mfma_f32_16x16x32_bf16 v[82:85], v[134:137], v[16:19], v[54:57]
	s_nop 2
	v_lshl_add_u64 v[54:55], v[68:69], 0, v[62:63]
	s_nop 1
	global_load_dwordx4 v[106:109], v[54:55], off
	v_lshl_add_u64 v[68:69], v[74:75], 0, s[0:1]
	global_load_dwordx4 v[110:113], v[24:25], off offset:320
	s_waitcnt vmcnt(2)
	v_mfma_f32_16x16x32_bf16 v[86:89], v[102:105], v[16:19], v[58:61]
	s_nop 2
	v_lshl_add_u64 v[60:61], v[68:69], 0, v[72:73]
	s_mov_b64 s[0:1], 0x180
	global_load_dwordx4 v[114:117], v[60:61], off
	v_lshl_add_u64 v[90:91], v[74:75], 0, s[0:1]
	s_mov_b64 s[0:1], 0x1c0
	v_lshl_add_u64 v[58:59], v[68:69], 0, v[70:71]
	s_nop 1
	global_load_dwordx4 v[118:121], v[58:59], off
	v_lshl_add_u64 v[56:57], v[68:69], 0, v[62:63]
	s_waitcnt vmcnt(3)
	v_mfma_f32_16x16x32_bf16 v[16:19], v[106:109], v[16:19], v[64:67]
	global_load_dwordx4 v[122:125], v[56:57], off
	v_lshl_add_u64 v[74:75], v[74:75], 0, s[0:1]
	s_movk_i32 s0, 0x7fc
	s_waitcnt vmcnt(3)
	v_mfma_f32_16x16x32_bf16 v[64:67], v[110:113], v[12:15], v[78:81]
	global_load_dwordx4 v[126:129], v[24:25], off offset:384
	s_waitcnt vmcnt(3)
	v_mfma_f32_16x16x32_bf16 v[78:81], v[114:117], v[12:15], v[82:85]
	s_waitcnt vmcnt(2)
	v_mfma_f32_16x16x32_bf16 v[82:85], v[118:121], v[12:15], v[86:89]
	s_nop 2
	s_waitcnt vmcnt(1)
	v_mfma_f32_16x16x32_bf16 v[12:15], v[122:125], v[12:15], v[16:19]
	s_nop 2
	s_waitcnt vmcnt(0)
	v_mfma_f32_16x16x32_bf16 v[16:19], v[126:129], v[8:11], v[64:67]
	s_nop 2
	v_lshl_add_u64 v[64:65], v[90:91], 0, v[72:73]
	global_load_dwordx4 v[130:133], v[64:65], off
	v_lshl_add_u64 v[72:73], v[74:75], 0, v[72:73]
	v_lshl_add_u64 v[66:67], v[90:91], 0, v[70:71]
	global_load_dwordx4 v[134:137], v[66:67], off
	v_lshl_add_u64 v[68:69], v[90:91], 0, v[62:63]
	global_load_dwordx4 v[102:105], v[68:69], off
	v_lshl_add_u64 v[70:71], v[74:75], 0, v[70:71]
	v_lshl_add_u64 v[74:75], v[74:75], 0, v[62:63]
	global_load_dwordx4 v[106:109], v[24:25], off offset:448
	v_or_b32_e32 v62, 16, v26
	v_ashrrev_i32_e32 v63, 31, v62
	s_waitcnt vmcnt(3)
	v_mfma_f32_16x16x32_bf16 v[78:81], v[130:133], v[8:11], v[78:81]
	global_load_dwordx4 v[110:113], v[72:73], off
	s_waitcnt vmcnt(3)
	v_mfma_f32_16x16x32_bf16 v[82:85], v[134:137], v[8:11], v[82:85]
	global_load_dwordx4 v[114:117], v[70:71], off
	s_waitcnt vmcnt(3)
	v_mfma_f32_16x16x32_bf16 v[8:11], v[102:105], v[8:11], v[12:15]
	s_nop 2
	global_load_dwordx4 v[118:121], v[74:75], off
	s_waitcnt vmcnt(3)
	v_mfma_f32_16x16x32_bf16 v[12:15], v[106:109], v[4:7], v[16:19]
	s_nop 2
	s_waitcnt vmcnt(2)
	v_mfma_f32_16x16x32_bf16 v[16:19], v[110:113], v[4:7], v[78:81]
	s_nop 2
	s_waitcnt vmcnt(1)
	v_mfma_f32_16x16x32_bf16 v[78:81], v[114:117], v[4:7], v[82:85]
	s_nop 2
	s_waitcnt vmcnt(0)
	v_mfma_f32_16x16x32_bf16 v[4:7], v[118:121], v[4:7], v[8:11]
	s_nop 2
	v_lshlrev_b64 v[8:9], 7, v[26:27]
	v_lshl_add_u64 v[8:9], s[22:23], 0, v[8:9]
	v_lshl_add_u64 v[8:9], v[8:9], 0, v[2:3]
	v_cvt_pk_bf16_f32 v10, v12, v13
	v_cvt_pk_bf16_f32 v11, v14, v15
	v_cvt_pk_bf16_f32 v4, v4, v5
	v_cvt_pk_bf16_f32 v5, v6, v7
	global_store_dwordx2 v[8:9], v[10:11], off
	v_cvt_pk_bf16_f32 v10, v16, v17
	v_cvt_pk_bf16_f32 v11, v18, v19
	global_store_dwordx2 v[8:9], v[4:5], off offset:96
	v_lshlrev_b64 v[4:5], 9, v[62:63]
	global_store_dwordx2 v[8:9], v[10:11], off offset:32
	v_cvt_pk_bf16_f32 v10, v78, v79
	v_cvt_pk_bf16_f32 v11, v80, v81
	v_lshl_add_u64 v[4:5], s[24:25], 0, v[4:5]
	global_store_dwordx2 v[8:9], v[10:11], off offset:64
	v_lshl_add_u64 v[4:5], v[4:5], 0, v[28:29]
	v_bitop3_b32 v2, v26, s0, 16 bitop3:0xc8
	global_load_dwordx4 v[26:29], v[4:5], off
	global_load_dwordx4 v[78:81], v[4:5], off offset:64
	global_load_dwordx4 v[82:85], v[4:5], off offset:128
	global_load_dwordx4 v[86:89], v[4:5], off offset:192
	global_load_dwordx4 v[16:19], v[4:5], off offset:256
	global_load_dwordx4 v[12:15], v[4:5], off offset:320
	global_load_dwordx4 v[8:11], v[4:5], off offset:384
	s_nop 0
	global_load_dwordx4 v[4:7], v[4:5], off offset:448
	s_nop 0
	global_load_dwordx4 v[122:125], v[24:25], off
	global_load_dwordx4 v[126:129], v[30:31], off
	global_load_dwordx4 v[130:133], v[34:35], off
	s_waitcnt vmcnt(2)
	v_mfma_f32_16x16x32_bf16 v[90:93], v[122:125], v[26:29], 0
	global_load_dwordx4 v[134:137], v[32:33], off
	v_cmp_ne_u32_e64 s[2:3], s0, v2
	global_load_dwordx4 v[102:105], v[36:37], off
	s_waitcnt vmcnt(3)
	v_mfma_f32_16x16x32_bf16 v[94:97], v[126:129], v[26:29], 0
	v_cmp_eq_u32_e32 vcc, s0, v2
	s_waitcnt vmcnt(1)
	v_mfma_f32_16x16x32_bf16 v[30:33], v[134:137], v[26:29], 0
	v_mfma_f32_16x16x32_bf16 v[26:29], v[130:133], v[26:29], 0
	global_load_dwordx4 v[106:109], v[24:25], off offset:64
	s_waitcnt vmcnt(1)
	v_mfma_f32_16x16x32_bf16 v[26:29], v[102:105], v[78:81], v[26:29]
	global_load_dwordx4 v[110:113], v[24:25], off offset:128
	s_waitcnt vmcnt(1)
	v_mfma_f32_16x16x32_bf16 v[90:93], v[106:109], v[78:81], v[90:93]
	global_load_dwordx4 v[114:117], v[40:41], off
	s_nop 0
	global_load_dwordx4 v[118:121], v[38:39], off
	global_load_dwordx4 v[122:125], v[42:43], off
	s_nop 0
	global_load_dwordx4 v[126:129], v[44:45], off
	global_load_dwordx4 v[130:133], v[46:47], off
	global_load_dwordx4 v[134:137], v[24:25], off offset:192
	s_waitcnt vmcnt(4)
	v_mfma_f32_16x16x32_bf16 v[30:33], v[118:121], v[78:81], v[30:33]
	s_waitcnt vmcnt(2)
	v_mfma_f32_16x16x32_bf16 v[30:33], v[126:129], v[82:85], v[30:33]
	s_waitcnt vmcnt(1)
	v_mfma_f32_16x16x32_bf16 v[26:29], v[130:133], v[82:85], v[26:29]
	v_mfma_f32_16x16x32_bf16 v[34:37], v[110:113], v[82:85], v[90:93]
	global_load_dwordx4 v[102:105], v[52:53], off
	s_waitcnt vmcnt(1)
	v_mfma_f32_16x16x32_bf16 v[34:37], v[134:137], v[86:89], v[34:37]
	v_mfma_f32_16x16x32_bf16 v[94:97], v[114:117], v[78:81], v[94:97]
	v_mfma_f32_16x16x32_bf16 v[38:41], v[122:125], v[82:85], v[94:97]
	global_load_dwordx4 v[106:109], v[50:51], off
	global_load_dwordx4 v[110:113], v[48:49], off
	global_load_dwordx4 v[114:117], v[24:25], off offset:256
	s_waitcnt vmcnt(3)
	v_mfma_f32_16x16x32_bf16 v[38:41], v[102:105], v[86:89], v[38:41]
	global_load_dwordx4 v[118:121], v[20:21], off
	s_nop 0
	global_load_dwordx4 v[122:125], v[22:23], off
	s_waitcnt vmcnt(4)
	v_mfma_f32_16x16x32_bf16 v[30:33], v[106:109], v[86:89], v[30:33]
	global_load_dwordx4 v[126:129], v[54:55], off
	s_waitcnt vmcnt(4)
	v_mfma_f32_16x16x32_bf16 v[26:29], v[110:113], v[86:89], v[26:29]
	s_waitcnt vmcnt(3)
	v_mfma_f32_16x16x32_bf16 v[34:37], v[114:117], v[16:19], v[34:37]
	s_waitcnt vmcnt(1)
	v_mfma_f32_16x16x32_bf16 v[20:23], v[122:125], v[16:19], v[30:33]
	s_nop 2
	v_mfma_f32_16x16x32_bf16 v[38:41], v[118:121], v[16:19], v[38:41]
	global_load_dwordx4 v[130:133], v[24:25], off offset:320
	global_load_dwordx4 v[134:137], v[60:61], off
	s_waitcnt vmcnt(2)
	v_mfma_f32_16x16x32_bf16 v[16:19], v[126:129], v[16:19], v[26:29]
	s_nop 2
	s_waitcnt vmcnt(1)
	v_mfma_f32_16x16x32_bf16 v[26:29], v[130:133], v[12:15], v[34:37]
	s_nop 2
	global_load_dwordx4 v[102:105], v[58:59], off
	global_load_dwordx4 v[106:109], v[56:57], off
	s_waitcnt vmcnt(1)
	v_mfma_f32_16x16x32_bf16 v[20:23], v[102:105], v[12:15], v[20:23]
	v_mfma_f32_16x16x32_bf16 v[30:33], v[134:137], v[12:15], v[38:41]
	global_load_dwordx4 v[110:113], v[24:25], off offset:384
	global_load_dwordx4 v[114:117], v[64:65], off
	global_load_dwordx4 v[118:121], v[66:67], off
	s_waitcnt vmcnt(3)
	v_mfma_f32_16x16x32_bf16 v[12:15], v[106:109], v[12:15], v[16:19]
	s_nop 2
	global_load_dwordx4 v[122:125], v[68:69], off
	s_waitcnt vmcnt(3)
	v_mfma_f32_16x16x32_bf16 v[16:19], v[110:113], v[8:11], v[26:29]
	s_nop 2
	global_load_dwordx4 v[126:129], v[24:25], off offset:448
	s_waitcnt vmcnt(3)
	v_mfma_f32_16x16x32_bf16 v[26:29], v[114:117], v[8:11], v[30:33]
	s_nop 2
	global_load_dwordx4 v[130:133], v[72:73], off
	s_nop 6
	s_waitcnt vmcnt(3)
	v_mfma_f32_16x16x32_bf16 v[20:23], v[118:121], v[8:11], v[20:23]
	s_waitcnt vmcnt(2)
	v_mfma_f32_16x16x32_bf16 v[30:33], v[122:125], v[8:11], v[12:15]
	s_waitcnt vmcnt(1)
	v_mfma_f32_16x16x32_bf16 v[16:19], v[126:129], v[4:7], v[16:19]
	s_nop 7
	v_cvt_pk_bf16_f32 v2, v16, v17
	global_load_dwordx4 v[134:137], v[70:71], off
	v_cndmask_b32_e64 v2, v2, 0, vcc
	global_load_dwordx4 v[102:105], v[74:75], off
	s_waitcnt vmcnt(2)
	v_mfma_f32_16x16x32_bf16 v[12:15], v[130:133], v[4:7], v[26:29]
	s_waitcnt vmcnt(1)
	v_mfma_f32_16x16x32_bf16 v[8:11], v[134:137], v[4:7], v[20:23]
	s_nop 2
	v_mov_b64_e32 v[20:21], v[2:3]
	s_and_saveexec_b64 s[0:1], s[2:3]
	s_xor_b64 s[0:1], exec, s[0:1]
	v_cvt_pk_bf16_f32 v21, v18, v19
	v_mov_b32_e32 v20, v2
	v_cvt_pk_bf16_f32 v16, v12, v13
	s_andn2_saveexec_b64 s[0:1], s[0:1]
	v_mov_b32_e32 v16, 0
	s_or_b64 exec, exec, s[0:1]
	v_lshlrev_b32_e32 v2, 2, v76
	v_lshlrev_b64 v[12:13], 7, v[62:63]
	v_lshl_add_u64 v[12:13], s[22:23], 0, v[12:13]
	v_lshlrev_b32_e32 v2, 1, v2
	v_lshl_add_u64 v[12:13], v[12:13], 0, v[2:3]
	v_mov_b32_e32 v17, v3
	s_waitcnt vmcnt(0)
	v_mfma_f32_16x16x32_bf16 v[4:7], v[102:105], v[4:7], v[30:33]
	global_store_dwordx2 v[12:13], v[20:21], off
	s_and_saveexec_b64 s[0:1], s[2:3]
	s_xor_b64 s[0:1], exec, s[0:1]
	v_cvt_pk_bf16_f32 v17, v14, v15
	v_cvt_pk_bf16_f32 v2, v8, v9
	s_andn2_saveexec_b64 s[0:1], s[0:1]
	v_mov_b32_e32 v2, 0
	s_or_b64 exec, exec, s[0:1]
	v_mov_b64_e32 v[14:15], v[2:3]
	global_store_dwordx2 v[12:13], v[16:17], off offset:32
	s_and_saveexec_b64 s[0:1], s[2:3]
	s_xor_b64 s[0:1], exec, s[0:1]
	v_cvt_pk_bf16_f32 v15, v10, v11
	v_mov_b32_e32 v14, v2
	v_cvt_pk_bf16_f32 v8, v4, v5
	s_andn2_saveexec_b64 s[0:1], s[0:1]
	v_mov_b32_e32 v8, 0
	s_or_b64 exec, exec, s[0:1]
	v_cvt_pk_bf16_f32 v2, v6, v7
	v_cndmask_b32_e64 v9, v2, 0, vcc
	s_andn2_b64 vcc, exec, s[44:45]
	s_mov_b64 s[0:1], -1
	global_store_dwordx2 v[12:13], v[14:15], off offset:64
	global_store_dwordx2 v[12:13], v[8:9], off offset:96
	s_cbranch_vccnz .LBB0_1070
	s_andn2_b64 vcc, exec, s[16:17]
	s_cbranch_vccnz .LBB0_1069
	s_barrier
	s_branch .LBB0_1069
